# GEMM K-loops: priority raised in LDS-read/stage segments, dropped in MFMA blocks (instead of no setprio); rest = stack10
# speedup vs baseline: 1.0041x; 1.0041x over previous
; #define PG8_STAGE(bufoff, gbase, voff) do { _Pragma("unroll") for (int _i = 0; _i < 2; ++_i) \
;         __builtin_amdgcn_global_load_lds((const unsigned*)((const char*)(gbase) + (voff)[_i]), (PG8_LAS unsigned*)(lds + (bufoff) + ldsw + _i * 8192), 16, 0, 0); } while (0)
; #define PG8_LDA(dst, b, h) do { _Pragma("unroll") for (int m = 0; m < 4; ++m) _Pragma("unroll") for (int k = 0; k < 2; ++k) dst[m][k] = *(const PG8_LAS bf16x8*)(lds + PG8_SA(b, h) + aoff + m * 2048 + k * 1024); } while (0)
; #define PG8_LDB(dst, b, h) do { _Pragma("unroll") for (int n = 0; n < 2; ++n) _Pragma("unroll") for (int k = 0; k < 2; ++k) dst[n][k] = *(const PG8_LAS bf16x8*)(lds + PG8_SB(b, h) + boff + n * 2048 + k * 1024); } while (0)
; #define PG8_MMA(ai, bj, At, Bt) do { __builtin_amdgcn_s_setprio(1); _Pragma("unroll") for (int m = 0; m < 4; ++m) _Pragma("unroll") for (int n = 0; n < 2; ++n) _Pragma("unroll") for (int k = 0; k < 2; ++k) \
;         acc[ai][bj][m][n] = __builtin_amdgcn_mfma_f32_16x16x32_bf16(Bt[n][k], At[m][k], acc[ai][bj][m][n], 0, 0, 0); __builtin_amdgcn_s_setprio(0); } while (0)
; #define PG8_WAIT_V(n) asm volatile("s_waitcnt vmcnt(" #n ")" ::: "memory")
; #define PG8_WAIT_L(n) asm volatile("s_waitcnt lgkmcnt(" #n ")" ::: "memory")
; #define PG8_BAR __builtin_amdgcn_s_barrier()
; #define PG8_SCHED __builtin_amdgcn_sched_barrier(0)
; template <class Epi, class Sched, bool ALIGN_EPI = false, bool SP2 = false>
; __device__ __forceinline__ void gemm_phase(PG8_LAS unsigned char* lds, const Gemm g, const Sched& S, const Epi& E) {
;     ...
;             const bool last = (t == nt - 2);
;             const char* a1 = cA + (size_t)(t + 1) * kstep;
;             const char* a2 = last ? nA : cA + (size_t)(t + 2) * kstep; const char* b2 = last ? nB : cB + (size_t)(t + 2) * kstep;
;             const char* a3 = a2 + kstep; const char* b3 = b2 + kstep;
;             if (last && has_next) S.a_ready(nxt);
;             if constexpr (SP2) {
;             PG8_LDB(B0, 0, 0); PG8_LDB(B1, 0, 1); PG8_SCHED; PG8_LDA(At, 0, 0); PG8_STAGE(PG8_SA(1, 1), a1 + hstep, voffA);
;             PG8_WAIT_V(8); PG8_WAIT_L(0); PG8_BAR; PG8_MMA(0, 0, At, B0); PG8_MMA(0, 1, At, B1); PG8_BAR; PG8_SCHED;
;             PG8_LDA(At, 0, 1); PG8_STAGE(PG8_SB(0, 0), b2, voffB); PG8_STAGE(PG8_SB(0, 1), b2 + hstep, voffB); PG8_STAGE(PG8_SA(0, 0), a2, voffA);
.LBB0_143:
	s_setprio 1
	s_add_u32 s56, s4, 0xfffc0080
	s_addc_u32 s57, s5, -1
	s_add_i32 s63, 0, 0x10000
	s_cmp_eq_u32 s62, 12
	s_cselect_b32 s59, s31, s57
	s_cselect_b32 s58, s33, s56
	s_cselect_b32 s57, s34, s51
	s_cselect_b32 s56, s35, s49
	s_add_i32 s66, 0, 0x14000
	v_add_u32_e32 v140, s63, v249
	v_add_u32_e32 v156, s66, v249
	ds_read_b128 v[128:131], v140
	ds_read_b128 v[132:135], v140 offset:1024
	ds_read_b128 v[136:139], v140 offset:2048
	ds_read_b128 v[140:143], v140 offset:3072
	ds_read_b128 v[144:147], v156
	ds_read_b128 v[148:151], v156 offset:1024
	ds_read_b128 v[152:155], v156 offset:2048
	ds_read_b128 v[156:159], v156 offset:3072
	v_lshl_add_u64 v[178:179], s[4:5], 0, v[206:207]
	s_add_i32 m0, s11, 0xc000
	ds_read_b128 v[160:163], v245
	ds_read_b128 v[164:167], v245 offset:1024
	ds_read_b128 v[168:171], v245 offset:2048
	ds_read_b128 v[172:175], v245 offset:3072
	ds_read_b128 v[208:211], v245 offset:4096
	ds_read_b128 v[212:215], v245 offset:5120
	ds_read_b128 v[216:219], v245 offset:6144
	ds_read_b128 v[220:223], v245 offset:7168
	global_load_lds_dwordx4 v[178:179], off
	v_lshl_add_u64 v[178:179], s[4:5], 0, v[204:205]
	s_add_i32 m0, s11, 0xe000
	s_nop 0
	global_load_lds_dwordx4 v[178:179], off
	s_waitcnt vmcnt(8)
	s_waitcnt lgkmcnt(0)
	s_barrier
	s_setprio 0
	v_mfma_f32_16x16x32_bf16 v[124:127], v[128:131], v[160:163], v[124:127]
	v_mfma_f32_16x16x32_bf16 v[120:123], v[136:139], v[160:163], v[120:123]
	v_mfma_f32_16x16x32_bf16 v[108:111], v[128:131], v[168:171], v[108:111]
	v_mfma_f32_16x16x32_bf16 v[104:107], v[136:139], v[168:171], v[104:107]
	v_mfma_f32_16x16x32_bf16 v[92:95], v[128:131], v[208:211], v[92:95]
	v_mfma_f32_16x16x32_bf16 v[88:91], v[136:139], v[208:211], v[88:91]
	v_mfma_f32_16x16x32_bf16 v[76:79], v[128:131], v[216:219], v[76:79]
	v_mfma_f32_16x16x32_bf16 v[72:75], v[136:139], v[216:219], v[72:75]
	v_mfma_f32_16x16x32_bf16 v[124:127], v[132:135], v[164:167], v[124:127]
	v_mfma_f32_16x16x32_bf16 v[120:123], v[140:143], v[164:167], v[120:123]
	v_mfma_f32_16x16x32_bf16 v[108:111], v[132:135], v[172:175], v[108:111]
	v_mfma_f32_16x16x32_bf16 v[104:107], v[140:143], v[172:175], v[104:107]
	v_mfma_f32_16x16x32_bf16 v[92:95], v[132:135], v[212:215], v[92:95]
	v_mfma_f32_16x16x32_bf16 v[88:91], v[140:143], v[212:215], v[88:91]
	v_mfma_f32_16x16x32_bf16 v[76:79], v[132:135], v[220:223], v[76:79]
	v_mfma_f32_16x16x32_bf16 v[72:75], v[140:143], v[220:223], v[72:75]
	v_mfma_f32_16x16x32_bf16 v[116:119], v[144:147], v[160:163], v[116:119]
	v_mfma_f32_16x16x32_bf16 v[112:115], v[152:155], v[160:163], v[112:115]
	v_mfma_f32_16x16x32_bf16 v[100:103], v[144:147], v[168:171], v[100:103]
	v_mfma_f32_16x16x32_bf16 v[96:99], v[152:155], v[168:171], v[96:99]
	v_mfma_f32_16x16x32_bf16 v[84:87], v[144:147], v[208:211], v[84:87]
	v_mfma_f32_16x16x32_bf16 v[80:83], v[152:155], v[208:211], v[80:83]
	v_mfma_f32_16x16x32_bf16 v[68:71], v[144:147], v[216:219], v[68:71]
	v_mfma_f32_16x16x32_bf16 v[64:67], v[152:155], v[216:219], v[64:67]
	v_mfma_f32_16x16x32_bf16 v[116:119], v[148:151], v[164:167], v[116:119]
	v_mfma_f32_16x16x32_bf16 v[112:115], v[156:159], v[164:167], v[112:115]
	v_mfma_f32_16x16x32_bf16 v[100:103], v[148:151], v[172:175], v[100:103]
	v_mfma_f32_16x16x32_bf16 v[96:99], v[156:159], v[172:175], v[96:99]
	v_mfma_f32_16x16x32_bf16 v[84:87], v[148:151], v[212:215], v[84:87]
	v_mfma_f32_16x16x32_bf16 v[80:83], v[156:159], v[212:215], v[80:83]
	v_mfma_f32_16x16x32_bf16 v[68:71], v[148:151], v[220:223], v[68:71]
	v_mfma_f32_16x16x32_bf16 v[64:67], v[156:159], v[220:223], v[64:67]
	s_barrier
	s_setprio 1
	s_add_i32 s63, s63, s2
	v_lshl_add_u64 v[178:179], s[56:57], 0, v[198:199]
	s_mov_b32 m0, s63
	ds_read_b128 v[160:163], v245 offset:16384
	ds_read_b128 v[164:167], v245 offset:17408
	ds_read_b128 v[168:171], v245 offset:18432
	ds_read_b128 v[172:175], v245 offset:19456
	ds_read_b128 v[208:211], v245 offset:20480
	ds_read_b128 v[212:215], v245 offset:21504
	ds_read_b128 v[216:219], v245 offset:22528
	ds_read_b128 v[220:223], v245 offset:23552
	global_load_lds_dwordx4 v[178:179], off
	s_add_i32 m0, s63, 0x2000
	s_add_u32 s64, s56, 0x40000
	v_lshl_add_u64 v[224:225], s[56:57], 0, v[194:195]
	s_addc_u32 s65, s57, 0
	s_add_i32 s63, s66, s2
	global_load_lds_dwordx4 v[224:225], off
	v_lshl_add_u64 v[226:227], s[64:65], 0, v[198:199]
	s_mov_b32 m0, s63
	v_lshl_add_u64 v[228:229], s[58:59], 0, v[196:197]
	global_load_lds_dwordx4 v[226:227], off
	v_lshl_add_u64 v[226:227], s[64:65], 0, v[194:195]
	s_add_i32 m0, s63, 0x2000
	s_nop 0
	global_load_lds_dwordx4 v[226:227], off
	v_lshl_add_u64 v[226:227], s[58:59], 0, v[200:201]
	s_mov_b32 m0, s11
	s_nop 0
	global_load_lds_dwordx4 v[226:227], off
	s_mov_b32 m0, s20
	s_nop 0
	global_load_lds_dwordx4 v[228:229], off
	s_waitcnt vmcnt(8)
	s_waitcnt lgkmcnt(0)
	s_barrier
; #define PG8_STAGE(bufoff, gbase, voff) do { _Pragma("unroll") for (int _i = 0; _i < 2; ++_i) \
;         __builtin_amdgcn_global_load_lds((const unsigned*)((const char*)(gbase) + (voff)[_i]), (PG8_LAS unsigned*)(lds + (bufoff) + ldsw + _i * 8192), 16, 0, 0); } while (0)
; #define PG8_LDA(dst, b, h) do { _Pragma("unroll") for (int m = 0; m < 4; ++m) _Pragma("unroll") for (int k = 0; k < 2; ++k) dst[m][k] = *(const PG8_LAS bf16x8*)(lds + PG8_SA(b, h) + aoff + m * 2048 + k * 1024); } while (0)
; #define PG8_LDB(dst, b, h) do { _Pragma("unroll") for (int n = 0; n < 2; ++n) _Pragma("unroll") for (int k = 0; k < 2; ++k) dst[n][k] = *(const PG8_LAS bf16x8*)(lds + PG8_SB(b, h) + boff + n * 2048 + k * 1024); } while (0)
; #define PG8_MMA(ai, bj, At, Bt) do { __builtin_amdgcn_s_setprio(1); _Pragma("unroll") for (int m = 0; m < 4; ++m) _Pragma("unroll") for (int n = 0; n < 2; ++n) _Pragma("unroll") for (int k = 0; k < 2; ++k) \
;         acc[ai][bj][m][n] = __builtin_amdgcn_mfma_f32_16x16x32_bf16(Bt[n][k], At[m][k], acc[ai][bj][m][n], 0, 0, 0); __builtin_amdgcn_s_setprio(0); } while (0)
; #define PG8_WAIT_V(n) asm volatile("s_waitcnt vmcnt(" #n ")" ::: "memory")
; #define PG8_WAIT_L(n) asm volatile("s_waitcnt lgkmcnt(" #n ")" ::: "memory")
; #define PG8_BAR __builtin_amdgcn_s_barrier()
; #define PG8_SCHED __builtin_amdgcn_sched_barrier(0)
; template <class Epi, class Sched, bool ALIGN_EPI = false, bool SP2 = false>
; __device__ __forceinline__ void gemm_phase(PG8_LAS unsigned char* lds, const Gemm g, const Sched& S, const Epi& E) {
;     ...
;             PG8_LDA(At, 0, 1); PG8_STAGE(PG8_SB(0, 0), b2, voffB); PG8_STAGE(PG8_SB(0, 1), b2 + hstep, voffB); PG8_STAGE(PG8_SA(0, 0), a2, voffA);
;             PG8_WAIT_V(8); PG8_WAIT_L(0); PG8_BAR; PG8_MMA(1, 0, At, B0); PG8_MMA(1, 1, At, B1); PG8_BAR; PG8_SCHED;
;             PG8_LDB(B0, 1, 0); PG8_LDB(B1, 1, 1); PG8_SCHED; PG8_LDA(At, 1, 0); PG8_STAGE(PG8_SA(0, 1), a2 + hstep, voffA);
;             PG8_WAIT_V(8); PG8_WAIT_L(0); PG8_BAR; PG8_MMA(0, 0, At, B0); PG8_MMA(0, 1, At, B1); PG8_BAR; PG8_SCHED;
	s_setprio 0
	v_mfma_f32_16x16x32_bf16 v[60:63], v[128:131], v[160:163], v[60:63]
	v_mfma_f32_16x16x32_bf16 v[56:59], v[136:139], v[160:163], v[56:59]
	v_mfma_f32_16x16x32_bf16 v[48:51], v[128:131], v[168:171], v[48:51]
	v_mfma_f32_16x16x32_bf16 v[40:43], v[136:139], v[168:171], v[40:43]
	v_mfma_f32_16x16x32_bf16 v[32:35], v[128:131], v[208:211], v[32:35]
	v_mfma_f32_16x16x32_bf16 v[24:27], v[136:139], v[208:211], v[24:27]
	v_mfma_f32_16x16x32_bf16 v[16:19], v[128:131], v[216:219], v[16:19]
	v_mfma_f32_16x16x32_bf16 v[8:11], v[136:139], v[216:219], v[8:11]
	v_mfma_f32_16x16x32_bf16 v[60:63], v[132:135], v[164:167], v[60:63]
	v_mfma_f32_16x16x32_bf16 v[56:59], v[140:143], v[164:167], v[56:59]
	v_mfma_f32_16x16x32_bf16 v[48:51], v[132:135], v[172:175], v[48:51]
	v_mfma_f32_16x16x32_bf16 v[40:43], v[140:143], v[172:175], v[40:43]
	v_mfma_f32_16x16x32_bf16 v[32:35], v[132:135], v[212:215], v[32:35]
	v_mfma_f32_16x16x32_bf16 v[24:27], v[140:143], v[212:215], v[24:27]
	v_mfma_f32_16x16x32_bf16 v[16:19], v[132:135], v[220:223], v[16:19]
	v_mfma_f32_16x16x32_bf16 v[8:11], v[140:143], v[220:223], v[8:11]
	v_mfma_f32_16x16x32_bf16 v[52:55], v[144:147], v[160:163], v[52:55]
	v_mfma_f32_16x16x32_bf16 v[44:47], v[152:155], v[160:163], v[44:47]
	v_mfma_f32_16x16x32_bf16 v[36:39], v[144:147], v[168:171], v[36:39]
	v_mfma_f32_16x16x32_bf16 v[28:31], v[152:155], v[168:171], v[28:31]
	v_mfma_f32_16x16x32_bf16 v[20:23], v[144:147], v[208:211], v[20:23]
	v_mfma_f32_16x16x32_bf16 v[12:15], v[152:155], v[208:211], v[12:15]
	v_mfma_f32_16x16x32_bf16 v[4:7], v[144:147], v[216:219], v[4:7]
	v_mfma_f32_16x16x32_bf16 v[0:3], v[152:155], v[216:219], v[0:3]
	v_mfma_f32_16x16x32_bf16 v[52:55], v[148:151], v[164:167], v[52:55]
	v_mfma_f32_16x16x32_bf16 v[44:47], v[156:159], v[164:167], v[44:47]
	v_mfma_f32_16x16x32_bf16 v[36:39], v[148:151], v[172:175], v[36:39]
	v_mfma_f32_16x16x32_bf16 v[28:31], v[156:159], v[172:175], v[28:31]
	v_mfma_f32_16x16x32_bf16 v[20:23], v[148:151], v[212:215], v[20:23]
	v_mfma_f32_16x16x32_bf16 v[12:15], v[156:159], v[212:215], v[12:15]
	v_mfma_f32_16x16x32_bf16 v[4:7], v[148:151], v[220:223], v[4:7]
	v_mfma_f32_16x16x32_bf16 v[0:3], v[156:159], v[220:223], v[0:3]
	s_barrier
	s_setprio 1
	s_add_i32 s63, 0, 0x18000
	s_add_i32 s64, 0, 0x1c000
	v_add_u32_e32 v140, s63, v249
	v_add_u32_e32 v156, s64, v249
	ds_read_b128 v[128:131], v140
	ds_read_b128 v[132:135], v140 offset:1024
	ds_read_b128 v[136:139], v140 offset:2048
	ds_read_b128 v[140:143], v140 offset:3072
	ds_read_b128 v[144:147], v156
	ds_read_b128 v[148:151], v156 offset:1024
	ds_read_b128 v[152:155], v156 offset:2048
	ds_read_b128 v[156:159], v156 offset:3072
	s_add_u32 s58, s58, 0x40000
	s_addc_u32 s59, s59, 0
	s_mov_b32 m0, s21
	v_lshl_add_u64 v[230:231], s[58:59], 0, v[200:201]
	ds_read_b128 v[160:163], v245 offset:32768
	ds_read_b128 v[164:167], v245 offset:33792
	ds_read_b128 v[168:171], v245 offset:34816
	ds_read_b128 v[172:175], v245 offset:35840
	ds_read_b128 v[208:211], v245 offset:36864
	ds_read_b128 v[212:215], v245 offset:37888
	ds_read_b128 v[216:219], v245 offset:38912
	ds_read_b128 v[220:223], v245 offset:39936
	global_load_lds_dwordx4 v[230:231], off
	v_lshl_add_u64 v[230:231], s[58:59], 0, v[196:197]
	s_mov_b32 m0, s22
	s_nop 0
	global_load_lds_dwordx4 v[230:231], off
	s_waitcnt vmcnt(8)
	s_waitcnt lgkmcnt(0)
	s_barrier
	s_setprio 0
	v_mfma_f32_16x16x32_bf16 v[124:127], v[128:131], v[160:163], v[124:127]
	v_mfma_f32_16x16x32_bf16 v[120:123], v[136:139], v[160:163], v[120:123]
	v_mfma_f32_16x16x32_bf16 v[108:111], v[128:131], v[168:171], v[108:111]
	v_mfma_f32_16x16x32_bf16 v[104:107], v[136:139], v[168:171], v[104:107]
	v_mfma_f32_16x16x32_bf16 v[92:95], v[128:131], v[208:211], v[92:95]
	v_mfma_f32_16x16x32_bf16 v[88:91], v[136:139], v[208:211], v[88:91]
	v_mfma_f32_16x16x32_bf16 v[76:79], v[128:131], v[216:219], v[76:79]
	v_mfma_f32_16x16x32_bf16 v[72:75], v[136:139], v[216:219], v[72:75]
	v_mfma_f32_16x16x32_bf16 v[124:127], v[132:135], v[164:167], v[124:127]
	v_mfma_f32_16x16x32_bf16 v[120:123], v[140:143], v[164:167], v[120:123]
	v_mfma_f32_16x16x32_bf16 v[108:111], v[132:135], v[172:175], v[108:111]
	v_mfma_f32_16x16x32_bf16 v[104:107], v[140:143], v[172:175], v[104:107]
	v_mfma_f32_16x16x32_bf16 v[92:95], v[132:135], v[212:215], v[92:95]
	v_mfma_f32_16x16x32_bf16 v[88:91], v[140:143], v[212:215], v[88:91]
	v_mfma_f32_16x16x32_bf16 v[76:79], v[132:135], v[220:223], v[76:79]
	v_mfma_f32_16x16x32_bf16 v[72:75], v[140:143], v[220:223], v[72:75]
	v_mfma_f32_16x16x32_bf16 v[116:119], v[144:147], v[160:163], v[116:119]
	v_mfma_f32_16x16x32_bf16 v[112:115], v[152:155], v[160:163], v[112:115]
	v_mfma_f32_16x16x32_bf16 v[100:103], v[144:147], v[168:171], v[100:103]
	v_mfma_f32_16x16x32_bf16 v[96:99], v[152:155], v[168:171], v[96:99]
	v_mfma_f32_16x16x32_bf16 v[84:87], v[144:147], v[208:211], v[84:87]
	v_mfma_f32_16x16x32_bf16 v[80:83], v[152:155], v[208:211], v[80:83]
	v_mfma_f32_16x16x32_bf16 v[68:71], v[144:147], v[216:219], v[68:71]
	v_mfma_f32_16x16x32_bf16 v[64:67], v[152:155], v[216:219], v[64:67]
	v_mfma_f32_16x16x32_bf16 v[116:119], v[148:151], v[164:167], v[116:119]
	v_mfma_f32_16x16x32_bf16 v[112:115], v[156:159], v[164:167], v[112:115]
	v_mfma_f32_16x16x32_bf16 v[100:103], v[148:151], v[172:175], v[100:103]
	v_mfma_f32_16x16x32_bf16 v[96:99], v[156:159], v[172:175], v[96:99]
	v_mfma_f32_16x16x32_bf16 v[84:87], v[148:151], v[212:215], v[84:87]
	v_mfma_f32_16x16x32_bf16 v[80:83], v[156:159], v[212:215], v[80:83]
	v_mfma_f32_16x16x32_bf16 v[68:71], v[148:151], v[220:223], v[68:71]
	v_mfma_f32_16x16x32_bf16 v[64:67], v[156:159], v[220:223], v[64:67]
	s_barrier
; #define PG8_STAGE(bufoff, gbase, voff) do { _Pragma("unroll") for (int _i = 0; _i < 2; ++_i) \
;         __builtin_amdgcn_global_load_lds((const unsigned*)((const char*)(gbase) + (voff)[_i]), (PG8_LAS unsigned*)(lds + (bufoff) + ldsw + _i * 8192), 16, 0, 0); } while (0)
; #define PG8_LDA(dst, b, h) do { _Pragma("unroll") for (int m = 0; m < 4; ++m) _Pragma("unroll") for (int k = 0; k < 2; ++k) dst[m][k] = *(const PG8_LAS bf16x8*)(lds + PG8_SA(b, h) + aoff + m * 2048 + k * 1024); } while (0)
; #define PG8_MMA(ai, bj, At, Bt) do { __builtin_amdgcn_s_setprio(1); _Pragma("unroll") for (int m = 0; m < 4; ++m) _Pragma("unroll") for (int n = 0; n < 2; ++n) _Pragma("unroll") for (int k = 0; k < 2; ++k) \
;         acc[ai][bj][m][n] = __builtin_amdgcn_mfma_f32_16x16x32_bf16(Bt[n][k], At[m][k], acc[ai][bj][m][n], 0, 0, 0); __builtin_amdgcn_s_setprio(0); } while (0)
; #define PG8_WAIT_V(n) asm volatile("s_waitcnt vmcnt(" #n ")" ::: "memory")
; #define PG8_WAIT_L(n) asm volatile("s_waitcnt lgkmcnt(" #n ")" ::: "memory")
; #define PG8_BAR __builtin_amdgcn_s_barrier()
; #define PG8_SCHED __builtin_amdgcn_sched_barrier(0)
; template <class Epi, class Sched, bool ALIGN_EPI = false, bool SP2 = false>
; __device__ __forceinline__ void gemm_phase(PG8_LAS unsigned char* lds, const Gemm g, const Sched& S, const Epi& E) {
;     ...
;             PG8_LDA(At, 1, 1); PG8_STAGE(PG8_SB(1, 0), b3, voffB); PG8_STAGE(PG8_SB(1, 1), b3 + hstep, voffB); PG8_STAGE(PG8_SA(1, 0), a3, voffA);
;             PG8_WAIT_V(8); PG8_WAIT_L(0); PG8_BAR; PG8_MMA(1, 0, At, B0); PG8_MMA(1, 1, At, B1); PG8_BAR; PG8_SCHED;
	s_setprio 1
	s_add_i32 s58, s63, s2
	v_lshl_add_u64 v[178:179], v[178:179], 0, s[36:37]
	s_mov_b32 m0, s58
	ds_read_b128 v[160:163], v245 offset:49152
	ds_read_b128 v[164:167], v245 offset:50176
	ds_read_b128 v[168:171], v245 offset:51200
	ds_read_b128 v[172:175], v245 offset:52224
	ds_read_b128 v[208:211], v245 offset:53248
	ds_read_b128 v[212:215], v245 offset:54272
	ds_read_b128 v[216:219], v245 offset:55296
	ds_read_b128 v[220:223], v245 offset:56320
	global_load_lds_dwordx4 v[178:179], off
	s_add_i32 m0, s58, 0x2000
	s_add_u32 s56, s56, 0x40080
	v_lshl_add_u64 v[178:179], v[224:225], 0, s[36:37]
	s_addc_u32 s57, s57, 0
	s_add_i32 s58, s64, s2
	global_load_lds_dwordx4 v[178:179], off
	v_lshl_add_u64 v[178:179], s[56:57], 0, v[198:199]
	s_mov_b32 m0, s58
	s_nop 0
	global_load_lds_dwordx4 v[178:179], off
	v_lshl_add_u64 v[178:179], s[56:57], 0, v[194:195]
	s_add_i32 m0, s58, 0x2000
	s_nop 0
	global_load_lds_dwordx4 v[178:179], off
	v_lshl_add_u64 v[178:179], v[226:227], 0, s[36:37]
	s_mov_b32 m0, s24
	s_nop 0
	global_load_lds_dwordx4 v[178:179], off
	v_lshl_add_u64 v[178:179], v[228:229], 0, s[36:37]
	s_mov_b32 m0, s25
	s_nop 0
	global_load_lds_dwordx4 v[178:179], off
	s_waitcnt vmcnt(8)
	s_waitcnt lgkmcnt(0)
	s_barrier
	s_setprio 0
	v_mfma_f32_16x16x32_bf16 v[60:63], v[128:131], v[160:163], v[60:63]
	v_mfma_f32_16x16x32_bf16 v[56:59], v[136:139], v[160:163], v[56:59]
	v_mfma_f32_16x16x32_bf16 v[48:51], v[128:131], v[168:171], v[48:51]
	v_mfma_f32_16x16x32_bf16 v[40:43], v[136:139], v[168:171], v[40:43]
	v_mfma_f32_16x16x32_bf16 v[32:35], v[128:131], v[208:211], v[32:35]
	v_mfma_f32_16x16x32_bf16 v[24:27], v[136:139], v[208:211], v[24:27]
	v_mfma_f32_16x16x32_bf16 v[16:19], v[128:131], v[216:219], v[16:19]
	v_mfma_f32_16x16x32_bf16 v[8:11], v[136:139], v[216:219], v[8:11]
	v_mfma_f32_16x16x32_bf16 v[60:63], v[132:135], v[164:167], v[60:63]
	v_mfma_f32_16x16x32_bf16 v[56:59], v[140:143], v[164:167], v[56:59]
	v_mfma_f32_16x16x32_bf16 v[48:51], v[132:135], v[172:175], v[48:51]
	v_mfma_f32_16x16x32_bf16 v[40:43], v[140:143], v[172:175], v[40:43]
	v_mfma_f32_16x16x32_bf16 v[32:35], v[132:135], v[212:215], v[32:35]
	v_mfma_f32_16x16x32_bf16 v[24:27], v[140:143], v[212:215], v[24:27]
	v_mfma_f32_16x16x32_bf16 v[16:19], v[132:135], v[220:223], v[16:19]
	v_mfma_f32_16x16x32_bf16 v[8:11], v[140:143], v[220:223], v[8:11]
	v_mfma_f32_16x16x32_bf16 v[52:55], v[144:147], v[160:163], v[52:55]
	v_mfma_f32_16x16x32_bf16 v[44:47], v[152:155], v[160:163], v[44:47]
	v_mfma_f32_16x16x32_bf16 v[36:39], v[144:147], v[168:171], v[36:39]
	v_mfma_f32_16x16x32_bf16 v[28:31], v[152:155], v[168:171], v[28:31]
	v_mfma_f32_16x16x32_bf16 v[20:23], v[144:147], v[208:211], v[20:23]
	v_mfma_f32_16x16x32_bf16 v[12:15], v[152:155], v[208:211], v[12:15]
	v_mfma_f32_16x16x32_bf16 v[4:7], v[144:147], v[216:219], v[4:7]
	v_mfma_f32_16x16x32_bf16 v[0:3], v[152:155], v[216:219], v[0:3]
	v_mfma_f32_16x16x32_bf16 v[52:55], v[148:151], v[164:167], v[52:55]
	v_mfma_f32_16x16x32_bf16 v[44:47], v[156:159], v[164:167], v[44:47]
	v_mfma_f32_16x16x32_bf16 v[36:39], v[148:151], v[172:175], v[36:39]
	v_mfma_f32_16x16x32_bf16 v[28:31], v[156:159], v[172:175], v[28:31]
	v_mfma_f32_16x16x32_bf16 v[20:23], v[148:151], v[212:215], v[20:23]
	v_mfma_f32_16x16x32_bf16 v[12:15], v[156:159], v[212:215], v[12:15]
	v_mfma_f32_16x16x32_bf16 v[4:7], v[148:151], v[220:223], v[4:7]
	v_mfma_f32_16x16x32_bf16 v[0:3], v[156:159], v[220:223], v[0:3]
	s_barrier
	s_add_i32 s62, s62, 2
	s_add_u32 s49, s49, 0x100
	s_addc_u32 s51, s51, 0
	s_add_u32 s4, s4, 0x100
	s_addc_u32 s5, s5, 0
	s_cmp_gt_u32 s62, 13
	s_cbranch_scc0 .LBB0_143
	s_and_b64 vcc, exec, s[44:45]
	s_cbranch_vccz .LBB0_146
	s_barrier

; #define PG8_STAGE(bufoff, gbase, voff) do { _Pragma("unroll") for (int _i = 0; _i < 2; ++_i) \
;         __builtin_amdgcn_global_load_lds((const unsigned*)((const char*)(gbase) + (voff)[_i]), (PG8_LAS unsigned*)(lds + (bufoff) + ldsw + _i * 8192), 16, 0, 0); } while (0)
; #define PG8_LDA(dst, b, h) do { _Pragma("unroll") for (int m = 0; m < 4; ++m) _Pragma("unroll") for (int k = 0; k < 2; ++k) dst[m][k] = *(const PG8_LAS bf16x8*)(lds + PG8_SA(b, h) + aoff + m * 2048 + k * 1024); } while (0)
; #define PG8_LDB(dst, b, h) do { _Pragma("unroll") for (int n = 0; n < 2; ++n) _Pragma("unroll") for (int k = 0; k < 2; ++k) dst[n][k] = *(const PG8_LAS bf16x8*)(lds + PG8_SB(b, h) + boff + n * 2048 + k * 1024); } while (0)
; #define PG8_MMA(ai, bj, At, Bt) do { __builtin_amdgcn_s_setprio(1); _Pragma("unroll") for (int m = 0; m < 4; ++m) _Pragma("unroll") for (int n = 0; n < 2; ++n) _Pragma("unroll") for (int k = 0; k < 2; ++k) \
;         acc[ai][bj][m][n] = __builtin_amdgcn_mfma_f32_16x16x32_bf16(Bt[n][k], At[m][k], acc[ai][bj][m][n], 0, 0, 0); __builtin_amdgcn_s_setprio(0); } while (0)
; #define PG8_WAIT_V(n) asm volatile("s_waitcnt vmcnt(" #n ")" ::: "memory")
; #define PG8_WAIT_L(n) asm volatile("s_waitcnt lgkmcnt(" #n ")" ::: "memory")
; #define PG8_BAR __builtin_amdgcn_s_barrier()
; #define PG8_SCHED __builtin_amdgcn_sched_barrier(0)
; template <class Epi, class Sched, bool ALIGN_EPI = false, bool SP2 = false>
; __device__ __forceinline__ void gemm_phase(PG8_LAS unsigned char* lds, const Gemm g, const Sched& S, const Epi& E) {
;     ...
;             const bool last = (t == nt - 2);
;             const char* a1 = cA + (size_t)(t + 1) * kstep;
;             const char* a2 = last ? nA : cA + (size_t)(t + 2) * kstep; const char* b2 = last ? nB : cB + (size_t)(t + 2) * kstep;
;             const char* a3 = a2 + kstep; const char* b3 = b2 + kstep;
;             if (last && has_next) S.a_ready(nxt);
;             if constexpr (SP2) {
;             PG8_LDB(B0, 0, 0); PG8_LDB(B1, 0, 1); PG8_SCHED; PG8_LDA(At, 0, 0); PG8_STAGE(PG8_SA(1, 1), a1 + hstep, voffA);
;             PG8_WAIT_V(8); PG8_WAIT_L(0); PG8_BAR; PG8_MMA(0, 0, At, B0); PG8_MMA(0, 1, At, B1); PG8_BAR; PG8_SCHED;
;             PG8_LDA(At, 0, 1); PG8_STAGE(PG8_SB(0, 0), b2, voffB); PG8_STAGE(PG8_SB(0, 1), b2 + hstep, voffB); PG8_STAGE(PG8_SA(0, 0), a2, voffA);
.LBB0_265:
	s_setprio 1
	s_add_u32 s16, s0, 0xfffc0080
	s_addc_u32 s17, s1, -1
	s_add_i32 s25, 0, 0x10000
	s_cmp_eq_u32 s24, 12
	s_cselect_b32 s27, s11, s17
	s_cselect_b32 s26, s14, s16
	v_add_u32_e32 v146, s25, v149
	s_cselect_b32 s17, s20, s23
	s_cselect_b32 s16, s21, s22
	s_add_i32 s30, 0, 0x14000
	ds_read_b128 v[142:145], v146
	ds_read_b128 v[154:157], v146 offset:1024
	ds_read_b128 v[158:161], v146 offset:2048
	ds_read_b128 v[162:165], v146 offset:3072
	v_add_u32_e32 v146, s30, v149
	ds_read_b128 v[166:169], v146
	ds_read_b128 v[170:173], v146 offset:1024
	ds_read_b128 v[194:197], v146 offset:2048
	ds_read_b128 v[198:201], v146 offset:3072
	v_lshl_add_u64 v[146:147], s[0:1], 0, v[140:141]
	s_add_i32 m0, s54, 0xc000
	ds_read_b128 v[202:205], v153
	ds_read_b128 v[206:209], v153 offset:1024
	ds_read_b128 v[210:213], v153 offset:2048
	ds_read_b128 v[214:217], v153 offset:3072
	ds_read_b128 v[218:221], v153 offset:4096
	ds_read_b128 v[222:225], v153 offset:5120
	ds_read_b128 v[226:229], v153 offset:6144
	ds_read_b128 v[230:233], v153 offset:7168
	global_load_lds_dwordx4 v[146:147], off
	v_lshl_add_u64 v[146:147], s[0:1], 0, v[138:139]
	s_add_i32 m0, s54, 0xe000
	s_nop 0
	global_load_lds_dwordx4 v[146:147], off
	s_waitcnt vmcnt(8)
	s_waitcnt lgkmcnt(0)
	s_barrier
	s_setprio 0
	v_mfma_f32_16x16x32_bf16 v[124:127], v[142:145], v[202:205], v[124:127]
	v_mfma_f32_16x16x32_bf16 v[120:123], v[158:161], v[202:205], v[120:123]
	v_mfma_f32_16x16x32_bf16 v[108:111], v[142:145], v[210:213], v[108:111]
	v_mfma_f32_16x16x32_bf16 v[104:107], v[158:161], v[210:213], v[104:107]
	v_mfma_f32_16x16x32_bf16 v[92:95], v[142:145], v[218:221], v[92:95]
	v_mfma_f32_16x16x32_bf16 v[88:91], v[158:161], v[218:221], v[88:91]
	v_mfma_f32_16x16x32_bf16 v[76:79], v[142:145], v[226:229], v[76:79]
	v_mfma_f32_16x16x32_bf16 v[72:75], v[158:161], v[226:229], v[72:75]
	v_mfma_f32_16x16x32_bf16 v[124:127], v[154:157], v[206:209], v[124:127]
	v_mfma_f32_16x16x32_bf16 v[120:123], v[162:165], v[206:209], v[120:123]
	v_mfma_f32_16x16x32_bf16 v[108:111], v[154:157], v[214:217], v[108:111]
	v_mfma_f32_16x16x32_bf16 v[104:107], v[162:165], v[214:217], v[104:107]
	v_mfma_f32_16x16x32_bf16 v[92:95], v[154:157], v[222:225], v[92:95]
	v_mfma_f32_16x16x32_bf16 v[88:91], v[162:165], v[222:225], v[88:91]
	v_mfma_f32_16x16x32_bf16 v[76:79], v[154:157], v[230:233], v[76:79]
	v_mfma_f32_16x16x32_bf16 v[72:75], v[162:165], v[230:233], v[72:75]
	v_mfma_f32_16x16x32_bf16 v[116:119], v[166:169], v[202:205], v[116:119]
	v_mfma_f32_16x16x32_bf16 v[112:115], v[194:197], v[202:205], v[112:115]
	v_mfma_f32_16x16x32_bf16 v[100:103], v[166:169], v[210:213], v[100:103]
	v_mfma_f32_16x16x32_bf16 v[96:99], v[194:197], v[210:213], v[96:99]
	v_mfma_f32_16x16x32_bf16 v[84:87], v[166:169], v[218:221], v[84:87]
	v_mfma_f32_16x16x32_bf16 v[80:83], v[194:197], v[218:221], v[80:83]
	v_mfma_f32_16x16x32_bf16 v[68:71], v[166:169], v[226:229], v[68:71]
	v_mfma_f32_16x16x32_bf16 v[64:67], v[194:197], v[226:229], v[64:67]
	v_mfma_f32_16x16x32_bf16 v[116:119], v[170:173], v[206:209], v[116:119]
	v_mfma_f32_16x16x32_bf16 v[112:115], v[198:201], v[206:209], v[112:115]
	v_mfma_f32_16x16x32_bf16 v[100:103], v[170:173], v[214:217], v[100:103]
	v_mfma_f32_16x16x32_bf16 v[96:99], v[198:201], v[214:217], v[96:99]
	v_mfma_f32_16x16x32_bf16 v[84:87], v[170:173], v[222:225], v[84:87]
	v_mfma_f32_16x16x32_bf16 v[80:83], v[198:201], v[222:225], v[80:83]
	v_mfma_f32_16x16x32_bf16 v[68:71], v[170:173], v[230:233], v[68:71]
	v_mfma_f32_16x16x32_bf16 v[64:67], v[198:201], v[230:233], v[64:67]
	s_barrier
	s_setprio 1
	s_add_i32 s25, s25, s2
	v_lshl_add_u64 v[146:147], s[16:17], 0, v[132:133]
	s_mov_b32 m0, s25
	ds_read_b128 v[202:205], v153 offset:16384
	ds_read_b128 v[206:209], v153 offset:17408
	ds_read_b128 v[210:213], v153 offset:18432
	ds_read_b128 v[214:217], v153 offset:19456
	ds_read_b128 v[218:221], v153 offset:20480
	ds_read_b128 v[222:225], v153 offset:21504
	ds_read_b128 v[226:229], v153 offset:22528
	ds_read_b128 v[230:233], v153 offset:23552
	global_load_lds_dwordx4 v[146:147], off
	s_add_i32 m0, s25, 0x2000
	s_add_u32 s28, s16, 0x40000
	v_lshl_add_u64 v[174:175], s[16:17], 0, v[128:129]
	s_addc_u32 s29, s17, 0
	s_add_i32 s25, s30, s2
	global_load_lds_dwordx4 v[174:175], off
	v_lshl_add_u64 v[178:179], s[28:29], 0, v[132:133]
	s_mov_b32 m0, s25
	v_lshl_add_u64 v[234:235], s[26:27], 0, v[130:131]
	global_load_lds_dwordx4 v[178:179], off
	v_lshl_add_u64 v[178:179], s[28:29], 0, v[128:129]
	s_add_i32 m0, s25, 0x2000
	s_nop 0
	global_load_lds_dwordx4 v[178:179], off
	v_lshl_add_u64 v[178:179], s[26:27], 0, v[134:135]
	s_mov_b32 m0, s54
	s_nop 0
	global_load_lds_dwordx4 v[178:179], off
	s_mov_b32 m0, s55
	s_nop 0
	global_load_lds_dwordx4 v[234:235], off
	s_waitcnt vmcnt(8)
	s_waitcnt lgkmcnt(0)
	s_barrier
; #define PG8_STAGE(bufoff, gbase, voff) do { _Pragma("unroll") for (int _i = 0; _i < 2; ++_i) \
;         __builtin_amdgcn_global_load_lds((const unsigned*)((const char*)(gbase) + (voff)[_i]), (PG8_LAS unsigned*)(lds + (bufoff) + ldsw + _i * 8192), 16, 0, 0); } while (0)
; #define PG8_LDA(dst, b, h) do { _Pragma("unroll") for (int m = 0; m < 4; ++m) _Pragma("unroll") for (int k = 0; k < 2; ++k) dst[m][k] = *(const PG8_LAS bf16x8*)(lds + PG8_SA(b, h) + aoff + m * 2048 + k * 1024); } while (0)
; #define PG8_LDB(dst, b, h) do { _Pragma("unroll") for (int n = 0; n < 2; ++n) _Pragma("unroll") for (int k = 0; k < 2; ++k) dst[n][k] = *(const PG8_LAS bf16x8*)(lds + PG8_SB(b, h) + boff + n * 2048 + k * 1024); } while (0)
; #define PG8_MMA(ai, bj, At, Bt) do { __builtin_amdgcn_s_setprio(1); _Pragma("unroll") for (int m = 0; m < 4; ++m) _Pragma("unroll") for (int n = 0; n < 2; ++n) _Pragma("unroll") for (int k = 0; k < 2; ++k) \
;         acc[ai][bj][m][n] = __builtin_amdgcn_mfma_f32_16x16x32_bf16(Bt[n][k], At[m][k], acc[ai][bj][m][n], 0, 0, 0); __builtin_amdgcn_s_setprio(0); } while (0)
; #define PG8_WAIT_V(n) asm volatile("s_waitcnt vmcnt(" #n ")" ::: "memory")
; #define PG8_WAIT_L(n) asm volatile("s_waitcnt lgkmcnt(" #n ")" ::: "memory")
; #define PG8_BAR __builtin_amdgcn_s_barrier()
; #define PG8_SCHED __builtin_amdgcn_sched_barrier(0)
; template <class Epi, class Sched, bool ALIGN_EPI = false, bool SP2 = false>
; __device__ __forceinline__ void gemm_phase(PG8_LAS unsigned char* lds, const Gemm g, const Sched& S, const Epi& E) {
;     ...
;             PG8_LDA(At, 0, 1); PG8_STAGE(PG8_SB(0, 0), b2, voffB); PG8_STAGE(PG8_SB(0, 1), b2 + hstep, voffB); PG8_STAGE(PG8_SA(0, 0), a2, voffA);
;             PG8_WAIT_V(8); PG8_WAIT_L(0); PG8_BAR; PG8_MMA(1, 0, At, B0); PG8_MMA(1, 1, At, B1); PG8_BAR; PG8_SCHED;
;             PG8_LDB(B0, 1, 0); PG8_LDB(B1, 1, 1); PG8_SCHED; PG8_LDA(At, 1, 0); PG8_STAGE(PG8_SA(0, 1), a2 + hstep, voffA);
;             PG8_WAIT_V(8); PG8_WAIT_L(0); PG8_BAR; PG8_MMA(0, 0, At, B0); PG8_MMA(0, 1, At, B1); PG8_BAR; PG8_SCHED;
	s_setprio 0
	v_mfma_f32_16x16x32_bf16 v[60:63], v[142:145], v[202:205], v[60:63]
	v_mfma_f32_16x16x32_bf16 v[56:59], v[158:161], v[202:205], v[56:59]
	v_mfma_f32_16x16x32_bf16 v[44:47], v[142:145], v[210:213], v[44:47]
	v_mfma_f32_16x16x32_bf16 v[40:43], v[158:161], v[210:213], v[40:43]
	v_mfma_f32_16x16x32_bf16 v[28:31], v[142:145], v[218:221], v[28:31]
	v_mfma_f32_16x16x32_bf16 v[24:27], v[158:161], v[218:221], v[24:27]
	v_mfma_f32_16x16x32_bf16 v[12:15], v[142:145], v[226:229], v[12:15]
	v_mfma_f32_16x16x32_bf16 v[8:11], v[158:161], v[226:229], v[8:11]
	v_mfma_f32_16x16x32_bf16 v[60:63], v[154:157], v[206:209], v[60:63]
	v_mfma_f32_16x16x32_bf16 v[56:59], v[162:165], v[206:209], v[56:59]
	v_mfma_f32_16x16x32_bf16 v[44:47], v[154:157], v[214:217], v[44:47]
	v_mfma_f32_16x16x32_bf16 v[40:43], v[162:165], v[214:217], v[40:43]
	v_mfma_f32_16x16x32_bf16 v[28:31], v[154:157], v[222:225], v[28:31]
	v_mfma_f32_16x16x32_bf16 v[24:27], v[162:165], v[222:225], v[24:27]
	v_mfma_f32_16x16x32_bf16 v[12:15], v[154:157], v[230:233], v[12:15]
	v_mfma_f32_16x16x32_bf16 v[8:11], v[162:165], v[230:233], v[8:11]
	v_mfma_f32_16x16x32_bf16 v[52:55], v[166:169], v[202:205], v[52:55]
	v_mfma_f32_16x16x32_bf16 v[48:51], v[194:197], v[202:205], v[48:51]
	v_mfma_f32_16x16x32_bf16 v[36:39], v[166:169], v[210:213], v[36:39]
	v_mfma_f32_16x16x32_bf16 v[32:35], v[194:197], v[210:213], v[32:35]
	v_mfma_f32_16x16x32_bf16 v[20:23], v[166:169], v[218:221], v[20:23]
	v_mfma_f32_16x16x32_bf16 v[16:19], v[194:197], v[218:221], v[16:19]
	v_mfma_f32_16x16x32_bf16 v[4:7], v[166:169], v[226:229], v[4:7]
	v_mfma_f32_16x16x32_bf16 v[0:3], v[194:197], v[226:229], v[0:3]
	v_mfma_f32_16x16x32_bf16 v[52:55], v[170:173], v[206:209], v[52:55]
	v_mfma_f32_16x16x32_bf16 v[48:51], v[198:201], v[206:209], v[48:51]
	v_mfma_f32_16x16x32_bf16 v[36:39], v[170:173], v[214:217], v[36:39]
	v_mfma_f32_16x16x32_bf16 v[32:35], v[198:201], v[214:217], v[32:35]
	v_mfma_f32_16x16x32_bf16 v[20:23], v[170:173], v[222:225], v[20:23]
	v_mfma_f32_16x16x32_bf16 v[16:19], v[198:201], v[222:225], v[16:19]
	v_mfma_f32_16x16x32_bf16 v[4:7], v[170:173], v[230:233], v[4:7]
	v_mfma_f32_16x16x32_bf16 v[0:3], v[198:201], v[230:233], v[0:3]
	s_barrier
	s_setprio 1
	s_add_i32 s25, 0, 0x18000
	v_add_u32_e32 v148, s25, v149
	s_add_i32 s28, 0, 0x1c000
	ds_read_b128 v[142:145], v148
	ds_read_b128 v[154:157], v148 offset:1024
	ds_read_b128 v[158:161], v148 offset:2048
	ds_read_b128 v[162:165], v148 offset:3072
	v_add_u32_e32 v148, s28, v149
	ds_read_b128 v[166:169], v148
	ds_read_b128 v[170:173], v148 offset:1024
	ds_read_b128 v[194:197], v148 offset:2048
	ds_read_b128 v[198:201], v148 offset:3072
	s_add_u32 s26, s26, 0x40000
	s_addc_u32 s27, s27, 0
	s_mov_b32 m0, s56
	v_lshl_add_u64 v[236:237], s[26:27], 0, v[134:135]
	ds_read_b128 v[202:205], v153 offset:32768
	ds_read_b128 v[206:209], v153 offset:33792
	ds_read_b128 v[210:213], v153 offset:34816
	ds_read_b128 v[214:217], v153 offset:35840
	ds_read_b128 v[218:221], v153 offset:36864
	ds_read_b128 v[222:225], v153 offset:37888
	ds_read_b128 v[226:229], v153 offset:38912
	ds_read_b128 v[230:233], v153 offset:39936
	global_load_lds_dwordx4 v[236:237], off
	v_lshl_add_u64 v[236:237], s[26:27], 0, v[130:131]
	s_mov_b32 m0, s57
	s_nop 0
	global_load_lds_dwordx4 v[236:237], off
	s_waitcnt vmcnt(8)
	s_waitcnt lgkmcnt(0)
	s_barrier
	s_setprio 0
	v_mfma_f32_16x16x32_bf16 v[124:127], v[142:145], v[202:205], v[124:127]
	v_mfma_f32_16x16x32_bf16 v[120:123], v[158:161], v[202:205], v[120:123]
	v_mfma_f32_16x16x32_bf16 v[108:111], v[142:145], v[210:213], v[108:111]
	v_mfma_f32_16x16x32_bf16 v[104:107], v[158:161], v[210:213], v[104:107]
	v_mfma_f32_16x16x32_bf16 v[92:95], v[142:145], v[218:221], v[92:95]
	v_mfma_f32_16x16x32_bf16 v[88:91], v[158:161], v[218:221], v[88:91]
	v_mfma_f32_16x16x32_bf16 v[76:79], v[142:145], v[226:229], v[76:79]
	v_mfma_f32_16x16x32_bf16 v[72:75], v[158:161], v[226:229], v[72:75]
	v_mfma_f32_16x16x32_bf16 v[124:127], v[154:157], v[206:209], v[124:127]
	v_mfma_f32_16x16x32_bf16 v[120:123], v[162:165], v[206:209], v[120:123]
	v_mfma_f32_16x16x32_bf16 v[108:111], v[154:157], v[214:217], v[108:111]
	v_mfma_f32_16x16x32_bf16 v[104:107], v[162:165], v[214:217], v[104:107]
	v_mfma_f32_16x16x32_bf16 v[92:95], v[154:157], v[222:225], v[92:95]
	v_mfma_f32_16x16x32_bf16 v[88:91], v[162:165], v[222:225], v[88:91]
	v_mfma_f32_16x16x32_bf16 v[76:79], v[154:157], v[230:233], v[76:79]
	v_mfma_f32_16x16x32_bf16 v[72:75], v[162:165], v[230:233], v[72:75]
	v_mfma_f32_16x16x32_bf16 v[116:119], v[166:169], v[202:205], v[116:119]
	v_mfma_f32_16x16x32_bf16 v[112:115], v[194:197], v[202:205], v[112:115]
	v_mfma_f32_16x16x32_bf16 v[100:103], v[166:169], v[210:213], v[100:103]
	v_mfma_f32_16x16x32_bf16 v[96:99], v[194:197], v[210:213], v[96:99]
	v_mfma_f32_16x16x32_bf16 v[84:87], v[166:169], v[218:221], v[84:87]
	v_mfma_f32_16x16x32_bf16 v[80:83], v[194:197], v[218:221], v[80:83]
	v_mfma_f32_16x16x32_bf16 v[68:71], v[166:169], v[226:229], v[68:71]
	v_mfma_f32_16x16x32_bf16 v[64:67], v[194:197], v[226:229], v[64:67]
	v_mfma_f32_16x16x32_bf16 v[116:119], v[170:173], v[206:209], v[116:119]
	v_mfma_f32_16x16x32_bf16 v[112:115], v[198:201], v[206:209], v[112:115]
	v_mfma_f32_16x16x32_bf16 v[100:103], v[170:173], v[214:217], v[100:103]
	v_mfma_f32_16x16x32_bf16 v[96:99], v[198:201], v[214:217], v[96:99]
	v_mfma_f32_16x16x32_bf16 v[84:87], v[170:173], v[222:225], v[84:87]
	v_mfma_f32_16x16x32_bf16 v[80:83], v[198:201], v[222:225], v[80:83]
	v_mfma_f32_16x16x32_bf16 v[68:71], v[170:173], v[230:233], v[68:71]
	v_mfma_f32_16x16x32_bf16 v[64:67], v[198:201], v[230:233], v[64:67]
	s_barrier
; #define PG8_STAGE(bufoff, gbase, voff) do { _Pragma("unroll") for (int _i = 0; _i < 2; ++_i) \
;         __builtin_amdgcn_global_load_lds((const unsigned*)((const char*)(gbase) + (voff)[_i]), (PG8_LAS unsigned*)(lds + (bufoff) + ldsw + _i * 8192), 16, 0, 0); } while (0)
; #define PG8_LDA(dst, b, h) do { _Pragma("unroll") for (int m = 0; m < 4; ++m) _Pragma("unroll") for (int k = 0; k < 2; ++k) dst[m][k] = *(const PG8_LAS bf16x8*)(lds + PG8_SA(b, h) + aoff + m * 2048 + k * 1024); } while (0)
; #define PG8_MMA(ai, bj, At, Bt) do { __builtin_amdgcn_s_setprio(1); _Pragma("unroll") for (int m = 0; m < 4; ++m) _Pragma("unroll") for (int n = 0; n < 2; ++n) _Pragma("unroll") for (int k = 0; k < 2; ++k) \
;         acc[ai][bj][m][n] = __builtin_amdgcn_mfma_f32_16x16x32_bf16(Bt[n][k], At[m][k], acc[ai][bj][m][n], 0, 0, 0); __builtin_amdgcn_s_setprio(0); } while (0)
; #define PG8_WAIT_V(n) asm volatile("s_waitcnt vmcnt(" #n ")" ::: "memory")
; #define PG8_WAIT_L(n) asm volatile("s_waitcnt lgkmcnt(" #n ")" ::: "memory")
; #define PG8_BAR __builtin_amdgcn_s_barrier()
; #define PG8_SCHED __builtin_amdgcn_sched_barrier(0)
; template <class Epi, class Sched, bool ALIGN_EPI = false, bool SP2 = false>
; __device__ __forceinline__ void gemm_phase(PG8_LAS unsigned char* lds, const Gemm g, const Sched& S, const Epi& E) {
;     ...
;             PG8_LDA(At, 1, 1); PG8_STAGE(PG8_SB(1, 0), b3, voffB); PG8_STAGE(PG8_SB(1, 1), b3 + hstep, voffB); PG8_STAGE(PG8_SA(1, 0), a3, voffA);
;             PG8_WAIT_V(8); PG8_WAIT_L(0); PG8_BAR; PG8_MMA(1, 0, At, B0); PG8_MMA(1, 1, At, B1); PG8_BAR; PG8_SCHED;
	s_setprio 1
	s_add_i32 s25, s25, s2
	v_lshl_add_u64 v[146:147], v[146:147], 0, s[36:37]
	s_mov_b32 m0, s25
	ds_read_b128 v[202:205], v153 offset:49152
	ds_read_b128 v[206:209], v153 offset:50176
	ds_read_b128 v[210:213], v153 offset:51200
	ds_read_b128 v[214:217], v153 offset:52224
	ds_read_b128 v[218:221], v153 offset:53248
	ds_read_b128 v[222:225], v153 offset:54272
	ds_read_b128 v[226:229], v153 offset:55296
	ds_read_b128 v[230:233], v153 offset:56320
	global_load_lds_dwordx4 v[146:147], off
	s_add_i32 m0, s25, 0x2000
	s_add_u32 s16, s16, 0x40080
	v_lshl_add_u64 v[146:147], v[174:175], 0, s[36:37]
	s_addc_u32 s17, s17, 0
	s_add_i32 s25, s28, s2
	global_load_lds_dwordx4 v[146:147], off
	v_lshl_add_u64 v[146:147], s[16:17], 0, v[132:133]
	s_mov_b32 m0, s25
	s_nop 0
	global_load_lds_dwordx4 v[146:147], off
	v_lshl_add_u64 v[146:147], s[16:17], 0, v[128:129]
	s_add_i32 m0, s25, 0x2000
	s_nop 0
	global_load_lds_dwordx4 v[146:147], off
	v_lshl_add_u64 v[146:147], v[178:179], 0, s[36:37]
	s_mov_b32 m0, s59
	s_nop 0
	global_load_lds_dwordx4 v[146:147], off
	v_lshl_add_u64 v[146:147], v[234:235], 0, s[36:37]
	s_mov_b32 m0, s62
	s_nop 0
	global_load_lds_dwordx4 v[146:147], off
	s_waitcnt vmcnt(8)
	s_waitcnt lgkmcnt(0)
	s_barrier
	s_setprio 0
	v_mfma_f32_16x16x32_bf16 v[60:63], v[142:145], v[202:205], v[60:63]
	v_mfma_f32_16x16x32_bf16 v[56:59], v[158:161], v[202:205], v[56:59]
	v_mfma_f32_16x16x32_bf16 v[44:47], v[142:145], v[210:213], v[44:47]
	v_mfma_f32_16x16x32_bf16 v[40:43], v[158:161], v[210:213], v[40:43]
	v_mfma_f32_16x16x32_bf16 v[28:31], v[142:145], v[218:221], v[28:31]
	v_mfma_f32_16x16x32_bf16 v[24:27], v[158:161], v[218:221], v[24:27]
	v_mfma_f32_16x16x32_bf16 v[12:15], v[142:145], v[226:229], v[12:15]
	v_mfma_f32_16x16x32_bf16 v[8:11], v[158:161], v[226:229], v[8:11]
	v_mfma_f32_16x16x32_bf16 v[60:63], v[154:157], v[206:209], v[60:63]
	v_mfma_f32_16x16x32_bf16 v[56:59], v[162:165], v[206:209], v[56:59]
	v_mfma_f32_16x16x32_bf16 v[44:47], v[154:157], v[214:217], v[44:47]
	v_mfma_f32_16x16x32_bf16 v[40:43], v[162:165], v[214:217], v[40:43]
	v_mfma_f32_16x16x32_bf16 v[28:31], v[154:157], v[222:225], v[28:31]
	v_mfma_f32_16x16x32_bf16 v[24:27], v[162:165], v[222:225], v[24:27]
	v_mfma_f32_16x16x32_bf16 v[12:15], v[154:157], v[230:233], v[12:15]
	v_mfma_f32_16x16x32_bf16 v[8:11], v[162:165], v[230:233], v[8:11]
	v_mfma_f32_16x16x32_bf16 v[52:55], v[166:169], v[202:205], v[52:55]
	v_mfma_f32_16x16x32_bf16 v[48:51], v[194:197], v[202:205], v[48:51]
	v_mfma_f32_16x16x32_bf16 v[36:39], v[166:169], v[210:213], v[36:39]
	v_mfma_f32_16x16x32_bf16 v[32:35], v[194:197], v[210:213], v[32:35]
	v_mfma_f32_16x16x32_bf16 v[20:23], v[166:169], v[218:221], v[20:23]
	v_mfma_f32_16x16x32_bf16 v[16:19], v[194:197], v[218:221], v[16:19]
	v_mfma_f32_16x16x32_bf16 v[4:7], v[166:169], v[226:229], v[4:7]
	v_mfma_f32_16x16x32_bf16 v[0:3], v[194:197], v[226:229], v[0:3]
	v_mfma_f32_16x16x32_bf16 v[52:55], v[170:173], v[206:209], v[52:55]
	v_mfma_f32_16x16x32_bf16 v[48:51], v[198:201], v[206:209], v[48:51]
	v_mfma_f32_16x16x32_bf16 v[36:39], v[170:173], v[214:217], v[36:39]
	v_mfma_f32_16x16x32_bf16 v[32:35], v[198:201], v[214:217], v[32:35]
	v_mfma_f32_16x16x32_bf16 v[20:23], v[170:173], v[222:225], v[20:23]
	v_mfma_f32_16x16x32_bf16 v[16:19], v[198:201], v[222:225], v[16:19]
	v_mfma_f32_16x16x32_bf16 v[4:7], v[170:173], v[230:233], v[4:7]
	v_mfma_f32_16x16x32_bf16 v[0:3], v[198:201], v[230:233], v[0:3]
	s_barrier
	s_add_i32 s24, s24, 2
	s_add_u32 s22, s22, 0x100
	s_addc_u32 s23, s23, 0
	s_add_u32 s0, s0, 0x100
	s_addc_u32 s1, s1, 0
	s_cmp_gt_u32 s24, 13
	s_cbranch_scc0 .LBB0_265
	s_and_b64 vcc, exec, s[44:45]
	s_cbranch_vccz .LBB0_268
	s_barrier

; #define PG8_STAGE(bufoff, gbase, voff) do { _Pragma("unroll") for (int _i = 0; _i < 2; ++_i) \
;         __builtin_amdgcn_global_load_lds((const unsigned*)((const char*)(gbase) + (voff)[_i]), (PG8_LAS unsigned*)(lds + (bufoff) + ldsw + _i * 8192), 16, 0, 0); } while (0)
; #define PG8_LDA(dst, b, h) do { _Pragma("unroll") for (int m = 0; m < 4; ++m) _Pragma("unroll") for (int k = 0; k < 2; ++k) dst[m][k] = *(const PG8_LAS bf16x8*)(lds + PG8_SA(b, h) + aoff + m * 2048 + k * 1024); } while (0)
; #define PG8_LDB(dst, b, h) do { _Pragma("unroll") for (int n = 0; n < 2; ++n) _Pragma("unroll") for (int k = 0; k < 2; ++k) dst[n][k] = *(const PG8_LAS bf16x8*)(lds + PG8_SB(b, h) + boff + n * 2048 + k * 1024); } while (0)
; #define PG8_MMA(ai, bj, At, Bt) do { __builtin_amdgcn_s_setprio(1); _Pragma("unroll") for (int m = 0; m < 4; ++m) _Pragma("unroll") for (int n = 0; n < 2; ++n) _Pragma("unroll") for (int k = 0; k < 2; ++k) \
;         acc[ai][bj][m][n] = __builtin_amdgcn_mfma_f32_16x16x32_bf16(Bt[n][k], At[m][k], acc[ai][bj][m][n], 0, 0, 0); __builtin_amdgcn_s_setprio(0); } while (0)
; #define PG8_WAIT_V(n) asm volatile("s_waitcnt vmcnt(" #n ")" ::: "memory")
; #define PG8_WAIT_L(n) asm volatile("s_waitcnt lgkmcnt(" #n ")" ::: "memory")
; #define PG8_BAR __builtin_amdgcn_s_barrier()
; #define PG8_SCHED __builtin_amdgcn_sched_barrier(0)
; template <class Epi, class Sched, bool ALIGN_EPI = false, bool SP2 = false>
; __device__ __forceinline__ void gemm_phase(PG8_LAS unsigned char* lds, const Gemm g, const Sched& S, const Epi& E) {
;     ...
;             const bool last = (t == nt - 2);
;             const char* a1 = cA + (size_t)(t + 1) * kstep;
;             const char* a2 = last ? nA : cA + (size_t)(t + 2) * kstep; const char* b2 = last ? nB : cB + (size_t)(t + 2) * kstep;
;             const char* a3 = a2 + kstep; const char* b3 = b2 + kstep;
;             if (last && has_next) S.a_ready(nxt);
;             if constexpr (SP2) {
;             PG8_LDB(B0, 0, 0); PG8_LDB(B1, 0, 1); PG8_SCHED; PG8_LDA(At, 0, 0); PG8_STAGE(PG8_SA(1, 1), a1 + hstep, voffA);
;             PG8_WAIT_V(8); PG8_WAIT_L(0); PG8_BAR; PG8_MMA(0, 0, At, B0); PG8_MMA(0, 1, At, B1); PG8_BAR; PG8_SCHED;
;             PG8_LDA(At, 0, 1); PG8_STAGE(PG8_SB(0, 0), b2, voffB); PG8_STAGE(PG8_SB(0, 1), b2 + hstep, voffB); PG8_STAGE(PG8_SA(0, 0), a2, voffA);
.LBB0_558:
	s_setprio 1
	s_add_u32 s50, s48, 0xfffc0080
	s_addc_u32 s51, s49, -1
	s_add_i32 s56, 0, 0x10000
	s_cmp_eq_u32 s55, 12
	s_cselect_b32 s53, s33, s51
	s_cselect_b32 s52, s34, s50
	s_cselect_b32 s51, s35, s54
	s_cselect_b32 s50, s41, s43
	s_add_i32 s58, 0, 0x14000
	v_add_u32_e32 v124, s56, v201
	v_add_u32_e32 v168, s58, v201
	ds_read_b128 v[112:115], v124
	ds_read_b128 v[116:119], v124 offset:1024
	ds_read_b128 v[120:123], v124 offset:2048
	ds_read_b128 v[124:127], v124 offset:3072
	ds_read_b128 v[128:131], v168
	ds_read_b128 v[132:135], v168 offset:1024
	ds_read_b128 v[164:167], v168 offset:2048
	ds_read_b128 v[168:171], v168 offset:3072
	v_lshl_add_u64 v[178:179], s[48:49], 0, v[162:163]
	s_add_i32 m0, s21, 0xc000
	ds_read_b128 v[172:175], v203
	ds_read_b128 v[194:197], v203 offset:1024
	ds_read_b128 v[204:207], v203 offset:2048
	ds_read_b128 v[208:211], v203 offset:3072
	ds_read_b128 v[212:215], v203 offset:4096
	ds_read_b128 v[216:219], v203 offset:5120
	ds_read_b128 v[220:223], v203 offset:6144
	ds_read_b128 v[224:227], v203 offset:7168
	global_load_lds_dwordx4 v[178:179], off
	v_lshl_add_u64 v[178:179], s[48:49], 0, v[160:161]
	s_add_i32 m0, s21, 0xe000
	s_nop 0
	global_load_lds_dwordx4 v[178:179], off
	s_waitcnt vmcnt(8)
	s_waitcnt lgkmcnt(0)
	s_barrier
	s_setprio 0
	v_mfma_f32_16x16x32_bf16 v[148:151], v[112:115], v[172:175], v[148:151]
	v_mfma_f32_16x16x32_bf16 v[144:147], v[120:123], v[172:175], v[144:147]
	v_mfma_f32_16x16x32_bf16 v[108:111], v[112:115], v[204:207], v[108:111]
	v_mfma_f32_16x16x32_bf16 v[104:107], v[120:123], v[204:207], v[104:107]
	v_mfma_f32_16x16x32_bf16 v[92:95], v[112:115], v[212:215], v[92:95]
	v_mfma_f32_16x16x32_bf16 v[88:91], v[120:123], v[212:215], v[88:91]
	v_mfma_f32_16x16x32_bf16 v[76:79], v[112:115], v[220:223], v[76:79]
	v_mfma_f32_16x16x32_bf16 v[72:75], v[120:123], v[220:223], v[72:75]
	v_mfma_f32_16x16x32_bf16 v[148:151], v[116:119], v[194:197], v[148:151]
	v_mfma_f32_16x16x32_bf16 v[144:147], v[124:127], v[194:197], v[144:147]
	v_mfma_f32_16x16x32_bf16 v[108:111], v[116:119], v[208:211], v[108:111]
	v_mfma_f32_16x16x32_bf16 v[104:107], v[124:127], v[208:211], v[104:107]
	v_mfma_f32_16x16x32_bf16 v[92:95], v[116:119], v[216:219], v[92:95]
	v_mfma_f32_16x16x32_bf16 v[88:91], v[124:127], v[216:219], v[88:91]
	v_mfma_f32_16x16x32_bf16 v[76:79], v[116:119], v[224:227], v[76:79]
	v_mfma_f32_16x16x32_bf16 v[72:75], v[124:127], v[224:227], v[72:75]
	v_mfma_f32_16x16x32_bf16 v[140:143], v[128:131], v[172:175], v[140:143]
	v_mfma_f32_16x16x32_bf16 v[136:139], v[164:167], v[172:175], v[136:139]
	v_mfma_f32_16x16x32_bf16 v[100:103], v[128:131], v[204:207], v[100:103]
	v_mfma_f32_16x16x32_bf16 v[96:99], v[164:167], v[204:207], v[96:99]
	v_mfma_f32_16x16x32_bf16 v[84:87], v[128:131], v[212:215], v[84:87]
	v_mfma_f32_16x16x32_bf16 v[80:83], v[164:167], v[212:215], v[80:83]
	v_mfma_f32_16x16x32_bf16 v[68:71], v[128:131], v[220:223], v[68:71]
	v_mfma_f32_16x16x32_bf16 v[64:67], v[164:167], v[220:223], v[64:67]
	v_mfma_f32_16x16x32_bf16 v[140:143], v[132:135], v[194:197], v[140:143]
	v_mfma_f32_16x16x32_bf16 v[136:139], v[168:171], v[194:197], v[136:139]
	v_mfma_f32_16x16x32_bf16 v[100:103], v[132:135], v[208:211], v[100:103]
	v_mfma_f32_16x16x32_bf16 v[96:99], v[168:171], v[208:211], v[96:99]
	v_mfma_f32_16x16x32_bf16 v[84:87], v[132:135], v[216:219], v[84:87]
	v_mfma_f32_16x16x32_bf16 v[80:83], v[168:171], v[216:219], v[80:83]
	v_mfma_f32_16x16x32_bf16 v[68:71], v[132:135], v[224:227], v[68:71]
	v_mfma_f32_16x16x32_bf16 v[64:67], v[168:171], v[224:227], v[64:67]
	s_barrier
	s_setprio 1
	s_add_i32 s56, s56, s20
	v_lshl_add_u64 v[178:179], s[50:51], 0, v[156:157]
	s_mov_b32 m0, s56
	ds_read_b128 v[172:175], v203 offset:16384
	ds_read_b128 v[194:197], v203 offset:17408
	ds_read_b128 v[204:207], v203 offset:18432
	ds_read_b128 v[208:211], v203 offset:19456
	ds_read_b128 v[212:215], v203 offset:20480
	ds_read_b128 v[216:219], v203 offset:21504
	ds_read_b128 v[220:223], v203 offset:22528
	ds_read_b128 v[224:227], v203 offset:23552
	global_load_lds_dwordx4 v[178:179], off
	s_add_i32 m0, s56, 0x2000
	s_add_u32 s56, s50, 0x40000
	v_lshl_add_u64 v[198:199], s[50:51], 0, v[152:153]
	s_addc_u32 s57, s51, 0
	s_add_i32 s58, s58, s20
	global_load_lds_dwordx4 v[198:199], off
	v_lshl_add_u64 v[228:229], s[56:57], 0, v[156:157]
	s_mov_b32 m0, s58
	v_lshl_add_u64 v[230:231], s[52:53], 0, v[154:155]
	global_load_lds_dwordx4 v[228:229], off
	v_lshl_add_u64 v[228:229], s[56:57], 0, v[152:153]
	s_add_i32 m0, s58, 0x2000
	s_nop 0
	global_load_lds_dwordx4 v[228:229], off
	v_lshl_add_u64 v[228:229], s[52:53], 0, v[158:159]
	s_mov_b32 m0, s21
	s_nop 0
	global_load_lds_dwordx4 v[228:229], off
	s_mov_b32 m0, s22
	s_nop 0
	global_load_lds_dwordx4 v[230:231], off
	s_waitcnt vmcnt(8)
	s_waitcnt lgkmcnt(0)
	s_barrier
; #define PG8_STAGE(bufoff, gbase, voff) do { _Pragma("unroll") for (int _i = 0; _i < 2; ++_i) \
;         __builtin_amdgcn_global_load_lds((const unsigned*)((const char*)(gbase) + (voff)[_i]), (PG8_LAS unsigned*)(lds + (bufoff) + ldsw + _i * 8192), 16, 0, 0); } while (0)
; #define PG8_LDA(dst, b, h) do { _Pragma("unroll") for (int m = 0; m < 4; ++m) _Pragma("unroll") for (int k = 0; k < 2; ++k) dst[m][k] = *(const PG8_LAS bf16x8*)(lds + PG8_SA(b, h) + aoff + m * 2048 + k * 1024); } while (0)
; #define PG8_LDB(dst, b, h) do { _Pragma("unroll") for (int n = 0; n < 2; ++n) _Pragma("unroll") for (int k = 0; k < 2; ++k) dst[n][k] = *(const PG8_LAS bf16x8*)(lds + PG8_SB(b, h) + boff + n * 2048 + k * 1024); } while (0)
; #define PG8_MMA(ai, bj, At, Bt) do { __builtin_amdgcn_s_setprio(1); _Pragma("unroll") for (int m = 0; m < 4; ++m) _Pragma("unroll") for (int n = 0; n < 2; ++n) _Pragma("unroll") for (int k = 0; k < 2; ++k) \
;         acc[ai][bj][m][n] = __builtin_amdgcn_mfma_f32_16x16x32_bf16(Bt[n][k], At[m][k], acc[ai][bj][m][n], 0, 0, 0); __builtin_amdgcn_s_setprio(0); } while (0)
; #define PG8_WAIT_V(n) asm volatile("s_waitcnt vmcnt(" #n ")" ::: "memory")
; #define PG8_WAIT_L(n) asm volatile("s_waitcnt lgkmcnt(" #n ")" ::: "memory")
; #define PG8_BAR __builtin_amdgcn_s_barrier()
; #define PG8_SCHED __builtin_amdgcn_sched_barrier(0)
; template <class Epi, class Sched, bool ALIGN_EPI = false, bool SP2 = false>
; __device__ __forceinline__ void gemm_phase(PG8_LAS unsigned char* lds, const Gemm g, const Sched& S, const Epi& E) {
;     ...
;             PG8_LDA(At, 0, 1); PG8_STAGE(PG8_SB(0, 0), b2, voffB); PG8_STAGE(PG8_SB(0, 1), b2 + hstep, voffB); PG8_STAGE(PG8_SA(0, 0), a2, voffA);
;             PG8_WAIT_V(8); PG8_WAIT_L(0); PG8_BAR; PG8_MMA(1, 0, At, B0); PG8_MMA(1, 1, At, B1); PG8_BAR; PG8_SCHED;
;             PG8_LDB(B0, 1, 0); PG8_LDB(B1, 1, 1); PG8_SCHED; PG8_LDA(At, 1, 0); PG8_STAGE(PG8_SA(0, 1), a2 + hstep, voffA);
;             PG8_WAIT_V(8); PG8_WAIT_L(0); PG8_BAR; PG8_MMA(0, 0, At, B0); PG8_MMA(0, 1, At, B1); PG8_BAR; PG8_SCHED;
	s_setprio 0
	v_mfma_f32_16x16x32_bf16 v[60:63], v[112:115], v[172:175], v[60:63]
	v_mfma_f32_16x16x32_bf16 v[56:59], v[120:123], v[172:175], v[56:59]
	v_mfma_f32_16x16x32_bf16 v[44:47], v[112:115], v[204:207], v[44:47]
	v_mfma_f32_16x16x32_bf16 v[40:43], v[120:123], v[204:207], v[40:43]
	v_mfma_f32_16x16x32_bf16 v[28:31], v[112:115], v[212:215], v[28:31]
	v_mfma_f32_16x16x32_bf16 v[24:27], v[120:123], v[212:215], v[24:27]
	v_mfma_f32_16x16x32_bf16 v[12:15], v[112:115], v[220:223], v[12:15]
	v_mfma_f32_16x16x32_bf16 v[8:11], v[120:123], v[220:223], v[8:11]
	v_mfma_f32_16x16x32_bf16 v[60:63], v[116:119], v[194:197], v[60:63]
	v_mfma_f32_16x16x32_bf16 v[56:59], v[124:127], v[194:197], v[56:59]
	v_mfma_f32_16x16x32_bf16 v[44:47], v[116:119], v[208:211], v[44:47]
	v_mfma_f32_16x16x32_bf16 v[40:43], v[124:127], v[208:211], v[40:43]
	v_mfma_f32_16x16x32_bf16 v[28:31], v[116:119], v[216:219], v[28:31]
	v_mfma_f32_16x16x32_bf16 v[24:27], v[124:127], v[216:219], v[24:27]
	v_mfma_f32_16x16x32_bf16 v[12:15], v[116:119], v[224:227], v[12:15]
	v_mfma_f32_16x16x32_bf16 v[8:11], v[124:127], v[224:227], v[8:11]
	v_mfma_f32_16x16x32_bf16 v[52:55], v[128:131], v[172:175], v[52:55]
	v_mfma_f32_16x16x32_bf16 v[48:51], v[164:167], v[172:175], v[48:51]
	v_mfma_f32_16x16x32_bf16 v[36:39], v[128:131], v[204:207], v[36:39]
	v_mfma_f32_16x16x32_bf16 v[32:35], v[164:167], v[204:207], v[32:35]
	v_mfma_f32_16x16x32_bf16 v[20:23], v[128:131], v[212:215], v[20:23]
	v_mfma_f32_16x16x32_bf16 v[16:19], v[164:167], v[212:215], v[16:19]
	v_mfma_f32_16x16x32_bf16 v[4:7], v[128:131], v[220:223], v[4:7]
	v_mfma_f32_16x16x32_bf16 v[0:3], v[164:167], v[220:223], v[0:3]
	v_mfma_f32_16x16x32_bf16 v[52:55], v[132:135], v[194:197], v[52:55]
	v_mfma_f32_16x16x32_bf16 v[48:51], v[168:171], v[194:197], v[48:51]
	v_mfma_f32_16x16x32_bf16 v[36:39], v[132:135], v[208:211], v[36:39]
	v_mfma_f32_16x16x32_bf16 v[32:35], v[168:171], v[208:211], v[32:35]
	v_mfma_f32_16x16x32_bf16 v[20:23], v[132:135], v[216:219], v[20:23]
	v_mfma_f32_16x16x32_bf16 v[16:19], v[168:171], v[216:219], v[16:19]
	v_mfma_f32_16x16x32_bf16 v[4:7], v[132:135], v[224:227], v[4:7]
	v_mfma_f32_16x16x32_bf16 v[0:3], v[168:171], v[224:227], v[0:3]
	s_barrier
	s_setprio 1
	s_add_i32 s56, 0, 0x18000
	s_add_i32 s57, 0, 0x1c000
	v_add_u32_e32 v124, s56, v201
	v_add_u32_e32 v168, s57, v201
	ds_read_b128 v[112:115], v124
	ds_read_b128 v[116:119], v124 offset:1024
	ds_read_b128 v[120:123], v124 offset:2048
	ds_read_b128 v[124:127], v124 offset:3072
	ds_read_b128 v[128:131], v168
	ds_read_b128 v[132:135], v168 offset:1024
	ds_read_b128 v[164:167], v168 offset:2048
	ds_read_b128 v[168:171], v168 offset:3072
	s_add_u32 s52, s52, 0x40000
	s_addc_u32 s53, s53, 0
	s_mov_b32 m0, s23
	v_lshl_add_u64 v[232:233], s[52:53], 0, v[158:159]
	ds_read_b128 v[172:175], v203 offset:32768
	ds_read_b128 v[194:197], v203 offset:33792
	ds_read_b128 v[204:207], v203 offset:34816
	ds_read_b128 v[208:211], v203 offset:35840
	ds_read_b128 v[212:215], v203 offset:36864
	ds_read_b128 v[216:219], v203 offset:37888
	ds_read_b128 v[220:223], v203 offset:38912
	ds_read_b128 v[224:227], v203 offset:39936
	global_load_lds_dwordx4 v[232:233], off
	v_lshl_add_u64 v[232:233], s[52:53], 0, v[154:155]
	s_mov_b32 m0, s24
	s_nop 0
	global_load_lds_dwordx4 v[232:233], off
	s_waitcnt vmcnt(8)
	s_waitcnt lgkmcnt(0)
	s_barrier
	s_setprio 0
	v_mfma_f32_16x16x32_bf16 v[148:151], v[112:115], v[172:175], v[148:151]
	v_mfma_f32_16x16x32_bf16 v[144:147], v[120:123], v[172:175], v[144:147]
	v_mfma_f32_16x16x32_bf16 v[108:111], v[112:115], v[204:207], v[108:111]
	v_mfma_f32_16x16x32_bf16 v[104:107], v[120:123], v[204:207], v[104:107]
	v_mfma_f32_16x16x32_bf16 v[92:95], v[112:115], v[212:215], v[92:95]
	v_mfma_f32_16x16x32_bf16 v[88:91], v[120:123], v[212:215], v[88:91]
	v_mfma_f32_16x16x32_bf16 v[76:79], v[112:115], v[220:223], v[76:79]
	v_mfma_f32_16x16x32_bf16 v[72:75], v[120:123], v[220:223], v[72:75]
	v_mfma_f32_16x16x32_bf16 v[148:151], v[116:119], v[194:197], v[148:151]
	v_mfma_f32_16x16x32_bf16 v[144:147], v[124:127], v[194:197], v[144:147]
	v_mfma_f32_16x16x32_bf16 v[108:111], v[116:119], v[208:211], v[108:111]
	v_mfma_f32_16x16x32_bf16 v[104:107], v[124:127], v[208:211], v[104:107]
	v_mfma_f32_16x16x32_bf16 v[92:95], v[116:119], v[216:219], v[92:95]
	v_mfma_f32_16x16x32_bf16 v[88:91], v[124:127], v[216:219], v[88:91]
	v_mfma_f32_16x16x32_bf16 v[76:79], v[116:119], v[224:227], v[76:79]
	v_mfma_f32_16x16x32_bf16 v[72:75], v[124:127], v[224:227], v[72:75]
	v_mfma_f32_16x16x32_bf16 v[140:143], v[128:131], v[172:175], v[140:143]
	v_mfma_f32_16x16x32_bf16 v[136:139], v[164:167], v[172:175], v[136:139]
	v_mfma_f32_16x16x32_bf16 v[100:103], v[128:131], v[204:207], v[100:103]
	v_mfma_f32_16x16x32_bf16 v[96:99], v[164:167], v[204:207], v[96:99]
	v_mfma_f32_16x16x32_bf16 v[84:87], v[128:131], v[212:215], v[84:87]
	v_mfma_f32_16x16x32_bf16 v[80:83], v[164:167], v[212:215], v[80:83]
	v_mfma_f32_16x16x32_bf16 v[68:71], v[128:131], v[220:223], v[68:71]
	v_mfma_f32_16x16x32_bf16 v[64:67], v[164:167], v[220:223], v[64:67]
	v_mfma_f32_16x16x32_bf16 v[140:143], v[132:135], v[194:197], v[140:143]
	v_mfma_f32_16x16x32_bf16 v[136:139], v[168:171], v[194:197], v[136:139]
	v_mfma_f32_16x16x32_bf16 v[100:103], v[132:135], v[208:211], v[100:103]
	v_mfma_f32_16x16x32_bf16 v[96:99], v[168:171], v[208:211], v[96:99]
	v_mfma_f32_16x16x32_bf16 v[84:87], v[132:135], v[216:219], v[84:87]
	v_mfma_f32_16x16x32_bf16 v[80:83], v[168:171], v[216:219], v[80:83]
	v_mfma_f32_16x16x32_bf16 v[68:71], v[132:135], v[224:227], v[68:71]
	v_mfma_f32_16x16x32_bf16 v[64:67], v[168:171], v[224:227], v[64:67]
	s_barrier
; #define PG8_STAGE(bufoff, gbase, voff) do { _Pragma("unroll") for (int _i = 0; _i < 2; ++_i) \
;         __builtin_amdgcn_global_load_lds((const unsigned*)((const char*)(gbase) + (voff)[_i]), (PG8_LAS unsigned*)(lds + (bufoff) + ldsw + _i * 8192), 16, 0, 0); } while (0)
; #define PG8_LDA(dst, b, h) do { _Pragma("unroll") for (int m = 0; m < 4; ++m) _Pragma("unroll") for (int k = 0; k < 2; ++k) dst[m][k] = *(const PG8_LAS bf16x8*)(lds + PG8_SA(b, h) + aoff + m * 2048 + k * 1024); } while (0)
; #define PG8_MMA(ai, bj, At, Bt) do { __builtin_amdgcn_s_setprio(1); _Pragma("unroll") for (int m = 0; m < 4; ++m) _Pragma("unroll") for (int n = 0; n < 2; ++n) _Pragma("unroll") for (int k = 0; k < 2; ++k) \
;         acc[ai][bj][m][n] = __builtin_amdgcn_mfma_f32_16x16x32_bf16(Bt[n][k], At[m][k], acc[ai][bj][m][n], 0, 0, 0); __builtin_amdgcn_s_setprio(0); } while (0)
; #define PG8_WAIT_V(n) asm volatile("s_waitcnt vmcnt(" #n ")" ::: "memory")
; #define PG8_WAIT_L(n) asm volatile("s_waitcnt lgkmcnt(" #n ")" ::: "memory")
; #define PG8_BAR __builtin_amdgcn_s_barrier()
; #define PG8_SCHED __builtin_amdgcn_sched_barrier(0)
; template <class Epi, class Sched, bool ALIGN_EPI = false, bool SP2 = false>
; __device__ __forceinline__ void gemm_phase(PG8_LAS unsigned char* lds, const Gemm g, const Sched& S, const Epi& E) {
;     ...
;             PG8_LDA(At, 1, 1); PG8_STAGE(PG8_SB(1, 0), b3, voffB); PG8_STAGE(PG8_SB(1, 1), b3 + hstep, voffB); PG8_STAGE(PG8_SA(1, 0), a3, voffA);
;             PG8_WAIT_V(8); PG8_WAIT_L(0); PG8_BAR; PG8_MMA(1, 0, At, B0); PG8_MMA(1, 1, At, B1); PG8_BAR; PG8_SCHED;
	s_setprio 1
	s_add_i32 s52, s56, s20
	v_lshl_add_u64 v[178:179], v[178:179], 0, s[36:37]
	s_mov_b32 m0, s52
	ds_read_b128 v[172:175], v203 offset:49152
	ds_read_b128 v[194:197], v203 offset:50176
	ds_read_b128 v[204:207], v203 offset:51200
	ds_read_b128 v[208:211], v203 offset:52224
	ds_read_b128 v[212:215], v203 offset:53248
	ds_read_b128 v[216:219], v203 offset:54272
	ds_read_b128 v[220:223], v203 offset:55296
	ds_read_b128 v[224:227], v203 offset:56320
	global_load_lds_dwordx4 v[178:179], off
	s_add_i32 m0, s52, 0x2000
	s_add_u32 s50, s50, 0x40080
	v_lshl_add_u64 v[178:179], v[198:199], 0, s[36:37]
	s_addc_u32 s51, s51, 0
	s_add_i32 s52, s57, s20
	global_load_lds_dwordx4 v[178:179], off
	v_lshl_add_u64 v[178:179], s[50:51], 0, v[156:157]
	s_mov_b32 m0, s52
	s_nop 0
	global_load_lds_dwordx4 v[178:179], off
	v_lshl_add_u64 v[178:179], s[50:51], 0, v[152:153]
	s_add_i32 m0, s52, 0x2000
	s_nop 0
	global_load_lds_dwordx4 v[178:179], off
	v_lshl_add_u64 v[178:179], v[228:229], 0, s[36:37]
	s_mov_b32 m0, s28
	s_nop 0
	global_load_lds_dwordx4 v[178:179], off
	v_lshl_add_u64 v[178:179], v[230:231], 0, s[36:37]
	s_mov_b32 m0, s29
	s_nop 0
	global_load_lds_dwordx4 v[178:179], off
	s_waitcnt vmcnt(8)
	s_waitcnt lgkmcnt(0)
	s_barrier
	s_setprio 0
	v_mfma_f32_16x16x32_bf16 v[60:63], v[112:115], v[172:175], v[60:63]
	v_mfma_f32_16x16x32_bf16 v[56:59], v[120:123], v[172:175], v[56:59]
	v_mfma_f32_16x16x32_bf16 v[44:47], v[112:115], v[204:207], v[44:47]
	v_mfma_f32_16x16x32_bf16 v[40:43], v[120:123], v[204:207], v[40:43]
	v_mfma_f32_16x16x32_bf16 v[28:31], v[112:115], v[212:215], v[28:31]
	v_mfma_f32_16x16x32_bf16 v[24:27], v[120:123], v[212:215], v[24:27]
	v_mfma_f32_16x16x32_bf16 v[12:15], v[112:115], v[220:223], v[12:15]
	v_mfma_f32_16x16x32_bf16 v[8:11], v[120:123], v[220:223], v[8:11]
	v_mfma_f32_16x16x32_bf16 v[60:63], v[116:119], v[194:197], v[60:63]
	v_mfma_f32_16x16x32_bf16 v[56:59], v[124:127], v[194:197], v[56:59]
	v_mfma_f32_16x16x32_bf16 v[44:47], v[116:119], v[208:211], v[44:47]
	v_mfma_f32_16x16x32_bf16 v[40:43], v[124:127], v[208:211], v[40:43]
	v_mfma_f32_16x16x32_bf16 v[28:31], v[116:119], v[216:219], v[28:31]
	v_mfma_f32_16x16x32_bf16 v[24:27], v[124:127], v[216:219], v[24:27]
	v_mfma_f32_16x16x32_bf16 v[12:15], v[116:119], v[224:227], v[12:15]
	v_mfma_f32_16x16x32_bf16 v[8:11], v[124:127], v[224:227], v[8:11]
	v_mfma_f32_16x16x32_bf16 v[52:55], v[128:131], v[172:175], v[52:55]
	v_mfma_f32_16x16x32_bf16 v[48:51], v[164:167], v[172:175], v[48:51]
	v_mfma_f32_16x16x32_bf16 v[36:39], v[128:131], v[204:207], v[36:39]
	v_mfma_f32_16x16x32_bf16 v[32:35], v[164:167], v[204:207], v[32:35]
	v_mfma_f32_16x16x32_bf16 v[20:23], v[128:131], v[212:215], v[20:23]
	v_mfma_f32_16x16x32_bf16 v[16:19], v[164:167], v[212:215], v[16:19]
	v_mfma_f32_16x16x32_bf16 v[4:7], v[128:131], v[220:223], v[4:7]
	v_mfma_f32_16x16x32_bf16 v[0:3], v[164:167], v[220:223], v[0:3]
	v_mfma_f32_16x16x32_bf16 v[52:55], v[132:135], v[194:197], v[52:55]
	v_mfma_f32_16x16x32_bf16 v[48:51], v[168:171], v[194:197], v[48:51]
	v_mfma_f32_16x16x32_bf16 v[36:39], v[132:135], v[208:211], v[36:39]
	v_mfma_f32_16x16x32_bf16 v[32:35], v[168:171], v[208:211], v[32:35]
	v_mfma_f32_16x16x32_bf16 v[20:23], v[132:135], v[216:219], v[20:23]
	v_mfma_f32_16x16x32_bf16 v[16:19], v[168:171], v[216:219], v[16:19]
	v_mfma_f32_16x16x32_bf16 v[4:7], v[132:135], v[224:227], v[4:7]
	v_mfma_f32_16x16x32_bf16 v[0:3], v[168:171], v[224:227], v[0:3]
	s_barrier
	s_add_i32 s55, s55, 2
	s_add_u32 s43, s43, 0x100
	s_addc_u32 s54, s54, 0
	s_add_u32 s48, s48, 0x100
	s_addc_u32 s49, s49, 0
	s_cmp_gt_u32 s55, 13
	s_cbranch_scc0 .LBB0_558
	s_and_b64 vcc, exec, s[26:27]
	s_cbranch_vccz .LBB0_561
	s_barrier

; #define PG8_STAGE(bufoff, gbase, voff) do { _Pragma("unroll") for (int _i = 0; _i < 2; ++_i) \
;         __builtin_amdgcn_global_load_lds((const unsigned*)((const char*)(gbase) + (voff)[_i]), (PG8_LAS unsigned*)(lds + (bufoff) + ldsw + _i * 8192), 16, 0, 0); } while (0)
; #define PG8_LDA(dst, b, h) do { _Pragma("unroll") for (int m = 0; m < 4; ++m) _Pragma("unroll") for (int k = 0; k < 2; ++k) dst[m][k] = *(const PG8_LAS bf16x8*)(lds + PG8_SA(b, h) + aoff + m * 2048 + k * 1024); } while (0)
; #define PG8_LDB(dst, b, h) do { _Pragma("unroll") for (int n = 0; n < 2; ++n) _Pragma("unroll") for (int k = 0; k < 2; ++k) dst[n][k] = *(const PG8_LAS bf16x8*)(lds + PG8_SB(b, h) + boff + n * 2048 + k * 1024); } while (0)
; #define PG8_MMA(ai, bj, At, Bt) do { __builtin_amdgcn_s_setprio(1); _Pragma("unroll") for (int m = 0; m < 4; ++m) _Pragma("unroll") for (int n = 0; n < 2; ++n) _Pragma("unroll") for (int k = 0; k < 2; ++k) \
;         acc[ai][bj][m][n] = __builtin_amdgcn_mfma_f32_16x16x32_bf16(Bt[n][k], At[m][k], acc[ai][bj][m][n], 0, 0, 0); __builtin_amdgcn_s_setprio(0); } while (0)
; #define PG8_WAIT_V(n) asm volatile("s_waitcnt vmcnt(" #n ")" ::: "memory")
; #define PG8_WAIT_L(n) asm volatile("s_waitcnt lgkmcnt(" #n ")" ::: "memory")
; #define PG8_BAR __builtin_amdgcn_s_barrier()
; #define PG8_SCHED __builtin_amdgcn_sched_barrier(0)
; template <class Epi, class Sched, bool ALIGN_EPI = false, bool SP2 = false>
; __device__ __forceinline__ void gemm_phase(PG8_LAS unsigned char* lds, const Gemm g, const Sched& S, const Epi& E) {
;     ...
;             const bool last = (t == nt - 2);
;             const char* a1 = cA + (size_t)(t + 1) * kstep;
;             const char* a2 = last ? nA : cA + (size_t)(t + 2) * kstep; const char* b2 = last ? nB : cB + (size_t)(t + 2) * kstep;
;             const char* a3 = a2 + kstep; const char* b3 = b2 + kstep;
;             if (last && has_next) S.a_ready(nxt);
;             if constexpr (SP2) {
;             PG8_LDB(B0, 0, 0); PG8_LDB(B1, 0, 1); PG8_SCHED; PG8_LDA(At, 0, 0); PG8_STAGE(PG8_SA(1, 1), a1 + hstep, voffA);
;             PG8_WAIT_V(8); PG8_WAIT_L(0); PG8_BAR; PG8_MMA(0, 0, At, B0); PG8_MMA(0, 1, At, B1); PG8_BAR; PG8_SCHED;
;             PG8_LDA(At, 0, 1); PG8_STAGE(PG8_SB(0, 0), b2, voffB); PG8_STAGE(PG8_SB(0, 1), b2 + hstep, voffB); PG8_STAGE(PG8_SA(0, 0), a2, voffA);
.LBB0_659:
	s_setprio 1
	s_add_u32 s48, s46, 0xfffc0080
	s_addc_u32 s49, s47, -1
	s_add_i32 s54, 0, 0x10000
	s_cmp_eq_u32 s53, 12
	s_cselect_b32 s51, s33, s49
	s_cselect_b32 s50, s34, s48
	v_add_u32_e32 v141, s54, v148
	s_cselect_b32 s49, s27, s52
	s_cselect_b32 s48, s35, s41
	s_add_i32 s56, 0, 0x14000
	ds_read_b128 v[142:145], v141
	ds_read_b128 v[152:155], v141 offset:1024
	ds_read_b128 v[156:159], v141 offset:2048
	ds_read_b128 v[160:163], v141 offset:3072
	v_add_u32_e32 v141, s56, v148
	ds_read_b128 v[164:167], v141
	ds_read_b128 v[168:171], v141 offset:1024
	ds_read_b128 v[172:175], v141 offset:2048
	ds_read_b128 v[194:197], v141 offset:3072
	v_lshl_add_u64 v[178:179], s[46:47], 0, v[138:139]
	s_add_i32 m0, s21, 0xc000
	ds_read_b128 v[198:201], v151
	ds_read_b128 v[202:205], v151 offset:1024
	ds_read_b128 v[206:209], v151 offset:2048
	ds_read_b128 v[210:213], v151 offset:3072
	ds_read_b128 v[214:217], v151 offset:4096
	ds_read_b128 v[218:221], v151 offset:5120
	ds_read_b128 v[222:225], v151 offset:6144
	ds_read_b128 v[226:229], v151 offset:7168
	global_load_lds_dwordx4 v[178:179], off
	v_lshl_add_u64 v[178:179], s[46:47], 0, v[136:137]
	s_add_i32 m0, s21, 0xe000
	s_nop 0
	global_load_lds_dwordx4 v[178:179], off
	s_waitcnt vmcnt(8)
	s_waitcnt lgkmcnt(0)
	s_barrier
	s_setprio 0
	v_mfma_f32_16x16x32_bf16 v[124:127], v[142:145], v[198:201], v[124:127]
	v_mfma_f32_16x16x32_bf16 v[120:123], v[156:159], v[198:201], v[120:123]
	v_mfma_f32_16x16x32_bf16 v[108:111], v[142:145], v[206:209], v[108:111]
	v_mfma_f32_16x16x32_bf16 v[104:107], v[156:159], v[206:209], v[104:107]
	v_mfma_f32_16x16x32_bf16 v[92:95], v[142:145], v[214:217], v[92:95]
	v_mfma_f32_16x16x32_bf16 v[88:91], v[156:159], v[214:217], v[88:91]
	v_mfma_f32_16x16x32_bf16 v[76:79], v[142:145], v[222:225], v[76:79]
	v_mfma_f32_16x16x32_bf16 v[72:75], v[156:159], v[222:225], v[72:75]
	v_mfma_f32_16x16x32_bf16 v[124:127], v[152:155], v[202:205], v[124:127]
	v_mfma_f32_16x16x32_bf16 v[120:123], v[160:163], v[202:205], v[120:123]
	v_mfma_f32_16x16x32_bf16 v[108:111], v[152:155], v[210:213], v[108:111]
	v_mfma_f32_16x16x32_bf16 v[104:107], v[160:163], v[210:213], v[104:107]
	v_mfma_f32_16x16x32_bf16 v[92:95], v[152:155], v[218:221], v[92:95]
	v_mfma_f32_16x16x32_bf16 v[88:91], v[160:163], v[218:221], v[88:91]
	v_mfma_f32_16x16x32_bf16 v[76:79], v[152:155], v[226:229], v[76:79]
	v_mfma_f32_16x16x32_bf16 v[72:75], v[160:163], v[226:229], v[72:75]
	v_mfma_f32_16x16x32_bf16 v[116:119], v[164:167], v[198:201], v[116:119]
	v_mfma_f32_16x16x32_bf16 v[112:115], v[172:175], v[198:201], v[112:115]
	v_mfma_f32_16x16x32_bf16 v[100:103], v[164:167], v[206:209], v[100:103]
	v_mfma_f32_16x16x32_bf16 v[96:99], v[172:175], v[206:209], v[96:99]
	v_mfma_f32_16x16x32_bf16 v[84:87], v[164:167], v[214:217], v[84:87]
	v_mfma_f32_16x16x32_bf16 v[80:83], v[172:175], v[214:217], v[80:83]
	v_mfma_f32_16x16x32_bf16 v[68:71], v[164:167], v[222:225], v[68:71]
	v_mfma_f32_16x16x32_bf16 v[64:67], v[172:175], v[222:225], v[64:67]
	v_mfma_f32_16x16x32_bf16 v[116:119], v[168:171], v[202:205], v[116:119]
	v_mfma_f32_16x16x32_bf16 v[112:115], v[194:197], v[202:205], v[112:115]
	v_mfma_f32_16x16x32_bf16 v[100:103], v[168:171], v[210:213], v[100:103]
	v_mfma_f32_16x16x32_bf16 v[96:99], v[194:197], v[210:213], v[96:99]
	v_mfma_f32_16x16x32_bf16 v[84:87], v[168:171], v[218:221], v[84:87]
	v_mfma_f32_16x16x32_bf16 v[80:83], v[194:197], v[218:221], v[80:83]
	v_mfma_f32_16x16x32_bf16 v[68:71], v[168:171], v[226:229], v[68:71]
	v_mfma_f32_16x16x32_bf16 v[64:67], v[194:197], v[226:229], v[64:67]
	s_barrier
	s_setprio 1
	s_add_i32 s54, s54, s20
	v_lshl_add_u64 v[178:179], s[48:49], 0, v[132:133]
	s_mov_b32 m0, s54
	ds_read_b128 v[198:201], v151 offset:16384
	ds_read_b128 v[202:205], v151 offset:17408
	ds_read_b128 v[206:209], v151 offset:18432
	ds_read_b128 v[210:213], v151 offset:19456
	ds_read_b128 v[214:217], v151 offset:20480
	ds_read_b128 v[218:221], v151 offset:21504
	ds_read_b128 v[222:225], v151 offset:22528
	ds_read_b128 v[226:229], v151 offset:23552
	global_load_lds_dwordx4 v[178:179], off
	s_add_i32 m0, s54, 0x2000
	s_add_u32 s54, s48, 0x40000
	v_lshl_add_u64 v[230:231], s[48:49], 0, v[128:129]
	s_addc_u32 s55, s49, 0
	s_add_i32 s56, s56, s20
	global_load_lds_dwordx4 v[230:231], off
	v_lshl_add_u64 v[232:233], s[54:55], 0, v[132:133]
	s_mov_b32 m0, s56
	v_lshl_add_u64 v[234:235], s[50:51], 0, v[130:131]
	global_load_lds_dwordx4 v[232:233], off
	v_lshl_add_u64 v[232:233], s[54:55], 0, v[128:129]
	s_add_i32 m0, s56, 0x2000
	s_nop 0
	global_load_lds_dwordx4 v[232:233], off
	v_lshl_add_u64 v[232:233], s[50:51], 0, v[134:135]
	s_mov_b32 m0, s21
	s_nop 0
	global_load_lds_dwordx4 v[232:233], off
	s_mov_b32 m0, s22
	s_nop 0
	global_load_lds_dwordx4 v[234:235], off
	s_waitcnt vmcnt(8)
	s_waitcnt lgkmcnt(0)
	s_barrier
; #define PG8_STAGE(bufoff, gbase, voff) do { _Pragma("unroll") for (int _i = 0; _i < 2; ++_i) \
;         __builtin_amdgcn_global_load_lds((const unsigned*)((const char*)(gbase) + (voff)[_i]), (PG8_LAS unsigned*)(lds + (bufoff) + ldsw + _i * 8192), 16, 0, 0); } while (0)
; #define PG8_LDA(dst, b, h) do { _Pragma("unroll") for (int m = 0; m < 4; ++m) _Pragma("unroll") for (int k = 0; k < 2; ++k) dst[m][k] = *(const PG8_LAS bf16x8*)(lds + PG8_SA(b, h) + aoff + m * 2048 + k * 1024); } while (0)
; #define PG8_LDB(dst, b, h) do { _Pragma("unroll") for (int n = 0; n < 2; ++n) _Pragma("unroll") for (int k = 0; k < 2; ++k) dst[n][k] = *(const PG8_LAS bf16x8*)(lds + PG8_SB(b, h) + boff + n * 2048 + k * 1024); } while (0)
; #define PG8_MMA(ai, bj, At, Bt) do { __builtin_amdgcn_s_setprio(1); _Pragma("unroll") for (int m = 0; m < 4; ++m) _Pragma("unroll") for (int n = 0; n < 2; ++n) _Pragma("unroll") for (int k = 0; k < 2; ++k) \
;         acc[ai][bj][m][n] = __builtin_amdgcn_mfma_f32_16x16x32_bf16(Bt[n][k], At[m][k], acc[ai][bj][m][n], 0, 0, 0); __builtin_amdgcn_s_setprio(0); } while (0)
; #define PG8_WAIT_V(n) asm volatile("s_waitcnt vmcnt(" #n ")" ::: "memory")
; #define PG8_WAIT_L(n) asm volatile("s_waitcnt lgkmcnt(" #n ")" ::: "memory")
; #define PG8_BAR __builtin_amdgcn_s_barrier()
; #define PG8_SCHED __builtin_amdgcn_sched_barrier(0)
; template <class Epi, class Sched, bool ALIGN_EPI = false, bool SP2 = false>
; __device__ __forceinline__ void gemm_phase(PG8_LAS unsigned char* lds, const Gemm g, const Sched& S, const Epi& E) {
;     ...
;             PG8_LDA(At, 0, 1); PG8_STAGE(PG8_SB(0, 0), b2, voffB); PG8_STAGE(PG8_SB(0, 1), b2 + hstep, voffB); PG8_STAGE(PG8_SA(0, 0), a2, voffA);
;             PG8_WAIT_V(8); PG8_WAIT_L(0); PG8_BAR; PG8_MMA(1, 0, At, B0); PG8_MMA(1, 1, At, B1); PG8_BAR; PG8_SCHED;
;             PG8_LDB(B0, 1, 0); PG8_LDB(B1, 1, 1); PG8_SCHED; PG8_LDA(At, 1, 0); PG8_STAGE(PG8_SA(0, 1), a2 + hstep, voffA);
;             PG8_WAIT_V(8); PG8_WAIT_L(0); PG8_BAR; PG8_MMA(0, 0, At, B0); PG8_MMA(0, 1, At, B1); PG8_BAR; PG8_SCHED;
	s_setprio 0
	v_mfma_f32_16x16x32_bf16 v[60:63], v[142:145], v[198:201], v[60:63]
	v_mfma_f32_16x16x32_bf16 v[56:59], v[156:159], v[198:201], v[56:59]
	v_mfma_f32_16x16x32_bf16 v[44:47], v[142:145], v[206:209], v[44:47]
	v_mfma_f32_16x16x32_bf16 v[40:43], v[156:159], v[206:209], v[40:43]
	v_mfma_f32_16x16x32_bf16 v[28:31], v[142:145], v[214:217], v[28:31]
	v_mfma_f32_16x16x32_bf16 v[24:27], v[156:159], v[214:217], v[24:27]
	v_mfma_f32_16x16x32_bf16 v[12:15], v[142:145], v[222:225], v[12:15]
	v_mfma_f32_16x16x32_bf16 v[8:11], v[156:159], v[222:225], v[8:11]
	v_mfma_f32_16x16x32_bf16 v[60:63], v[152:155], v[202:205], v[60:63]
	v_mfma_f32_16x16x32_bf16 v[56:59], v[160:163], v[202:205], v[56:59]
	v_mfma_f32_16x16x32_bf16 v[44:47], v[152:155], v[210:213], v[44:47]
	v_mfma_f32_16x16x32_bf16 v[40:43], v[160:163], v[210:213], v[40:43]
	v_mfma_f32_16x16x32_bf16 v[28:31], v[152:155], v[218:221], v[28:31]
	v_mfma_f32_16x16x32_bf16 v[24:27], v[160:163], v[218:221], v[24:27]
	v_mfma_f32_16x16x32_bf16 v[12:15], v[152:155], v[226:229], v[12:15]
	v_mfma_f32_16x16x32_bf16 v[8:11], v[160:163], v[226:229], v[8:11]
	v_mfma_f32_16x16x32_bf16 v[52:55], v[164:167], v[198:201], v[52:55]
	v_mfma_f32_16x16x32_bf16 v[48:51], v[172:175], v[198:201], v[48:51]
	v_mfma_f32_16x16x32_bf16 v[36:39], v[164:167], v[206:209], v[36:39]
	v_mfma_f32_16x16x32_bf16 v[32:35], v[172:175], v[206:209], v[32:35]
	v_mfma_f32_16x16x32_bf16 v[20:23], v[164:167], v[214:217], v[20:23]
	v_mfma_f32_16x16x32_bf16 v[16:19], v[172:175], v[214:217], v[16:19]
	v_mfma_f32_16x16x32_bf16 v[4:7], v[164:167], v[222:225], v[4:7]
	v_mfma_f32_16x16x32_bf16 v[0:3], v[172:175], v[222:225], v[0:3]
	v_mfma_f32_16x16x32_bf16 v[52:55], v[168:171], v[202:205], v[52:55]
	v_mfma_f32_16x16x32_bf16 v[48:51], v[194:197], v[202:205], v[48:51]
	v_mfma_f32_16x16x32_bf16 v[36:39], v[168:171], v[210:213], v[36:39]
	v_mfma_f32_16x16x32_bf16 v[32:35], v[194:197], v[210:213], v[32:35]
	v_mfma_f32_16x16x32_bf16 v[20:23], v[168:171], v[218:221], v[20:23]
	v_mfma_f32_16x16x32_bf16 v[16:19], v[194:197], v[218:221], v[16:19]
	v_mfma_f32_16x16x32_bf16 v[4:7], v[168:171], v[226:229], v[4:7]
	v_mfma_f32_16x16x32_bf16 v[0:3], v[194:197], v[226:229], v[0:3]
	s_barrier
	s_setprio 1
	s_add_i32 s54, 0, 0x18000
	v_add_u32_e32 v141, s54, v148
	s_add_i32 s55, 0, 0x1c000
	ds_read_b128 v[142:145], v141
	ds_read_b128 v[152:155], v141 offset:1024
	ds_read_b128 v[156:159], v141 offset:2048
	ds_read_b128 v[160:163], v141 offset:3072
	v_add_u32_e32 v141, s55, v148
	ds_read_b128 v[164:167], v141
	ds_read_b128 v[168:171], v141 offset:1024
	ds_read_b128 v[172:175], v141 offset:2048
	ds_read_b128 v[194:197], v141 offset:3072
	s_add_u32 s50, s50, 0x40000
	s_addc_u32 s51, s51, 0
	s_mov_b32 m0, s23
	v_lshl_add_u64 v[236:237], s[50:51], 0, v[134:135]
	ds_read_b128 v[198:201], v151 offset:32768
	ds_read_b128 v[202:205], v151 offset:33792
	ds_read_b128 v[206:209], v151 offset:34816
	ds_read_b128 v[210:213], v151 offset:35840
	ds_read_b128 v[214:217], v151 offset:36864
	ds_read_b128 v[218:221], v151 offset:37888
	ds_read_b128 v[222:225], v151 offset:38912
	ds_read_b128 v[226:229], v151 offset:39936
	global_load_lds_dwordx4 v[236:237], off
	v_lshl_add_u64 v[236:237], s[50:51], 0, v[130:131]
	s_mov_b32 m0, s24
	s_nop 0
	global_load_lds_dwordx4 v[236:237], off
	s_waitcnt vmcnt(8)
	s_waitcnt lgkmcnt(0)
	s_barrier
	s_setprio 0
	v_mfma_f32_16x16x32_bf16 v[124:127], v[142:145], v[198:201], v[124:127]
	v_mfma_f32_16x16x32_bf16 v[120:123], v[156:159], v[198:201], v[120:123]
	v_mfma_f32_16x16x32_bf16 v[108:111], v[142:145], v[206:209], v[108:111]
	v_mfma_f32_16x16x32_bf16 v[104:107], v[156:159], v[206:209], v[104:107]
	v_mfma_f32_16x16x32_bf16 v[92:95], v[142:145], v[214:217], v[92:95]
	v_mfma_f32_16x16x32_bf16 v[88:91], v[156:159], v[214:217], v[88:91]
	v_mfma_f32_16x16x32_bf16 v[76:79], v[142:145], v[222:225], v[76:79]
	v_mfma_f32_16x16x32_bf16 v[72:75], v[156:159], v[222:225], v[72:75]
	v_mfma_f32_16x16x32_bf16 v[124:127], v[152:155], v[202:205], v[124:127]
	v_mfma_f32_16x16x32_bf16 v[120:123], v[160:163], v[202:205], v[120:123]
	v_mfma_f32_16x16x32_bf16 v[108:111], v[152:155], v[210:213], v[108:111]
	v_mfma_f32_16x16x32_bf16 v[104:107], v[160:163], v[210:213], v[104:107]
	v_mfma_f32_16x16x32_bf16 v[92:95], v[152:155], v[218:221], v[92:95]
	v_mfma_f32_16x16x32_bf16 v[88:91], v[160:163], v[218:221], v[88:91]
	v_mfma_f32_16x16x32_bf16 v[76:79], v[152:155], v[226:229], v[76:79]
	v_mfma_f32_16x16x32_bf16 v[72:75], v[160:163], v[226:229], v[72:75]
	v_mfma_f32_16x16x32_bf16 v[116:119], v[164:167], v[198:201], v[116:119]
	v_mfma_f32_16x16x32_bf16 v[112:115], v[172:175], v[198:201], v[112:115]
	v_mfma_f32_16x16x32_bf16 v[100:103], v[164:167], v[206:209], v[100:103]
	v_mfma_f32_16x16x32_bf16 v[96:99], v[172:175], v[206:209], v[96:99]
	v_mfma_f32_16x16x32_bf16 v[84:87], v[164:167], v[214:217], v[84:87]
	v_mfma_f32_16x16x32_bf16 v[80:83], v[172:175], v[214:217], v[80:83]
	v_mfma_f32_16x16x32_bf16 v[68:71], v[164:167], v[222:225], v[68:71]
	v_mfma_f32_16x16x32_bf16 v[64:67], v[172:175], v[222:225], v[64:67]
	v_mfma_f32_16x16x32_bf16 v[116:119], v[168:171], v[202:205], v[116:119]
	v_mfma_f32_16x16x32_bf16 v[112:115], v[194:197], v[202:205], v[112:115]
	v_mfma_f32_16x16x32_bf16 v[100:103], v[168:171], v[210:213], v[100:103]
	v_mfma_f32_16x16x32_bf16 v[96:99], v[194:197], v[210:213], v[96:99]
	v_mfma_f32_16x16x32_bf16 v[84:87], v[168:171], v[218:221], v[84:87]
	v_mfma_f32_16x16x32_bf16 v[80:83], v[194:197], v[218:221], v[80:83]
	v_mfma_f32_16x16x32_bf16 v[68:71], v[168:171], v[226:229], v[68:71]
	v_mfma_f32_16x16x32_bf16 v[64:67], v[194:197], v[226:229], v[64:67]
	s_barrier
; #define PG8_STAGE(bufoff, gbase, voff) do { _Pragma("unroll") for (int _i = 0; _i < 2; ++_i) \
;         __builtin_amdgcn_global_load_lds((const unsigned*)((const char*)(gbase) + (voff)[_i]), (PG8_LAS unsigned*)(lds + (bufoff) + ldsw + _i * 8192), 16, 0, 0); } while (0)
; #define PG8_LDA(dst, b, h) do { _Pragma("unroll") for (int m = 0; m < 4; ++m) _Pragma("unroll") for (int k = 0; k < 2; ++k) dst[m][k] = *(const PG8_LAS bf16x8*)(lds + PG8_SA(b, h) + aoff + m * 2048 + k * 1024); } while (0)
; #define PG8_MMA(ai, bj, At, Bt) do { __builtin_amdgcn_s_setprio(1); _Pragma("unroll") for (int m = 0; m < 4; ++m) _Pragma("unroll") for (int n = 0; n < 2; ++n) _Pragma("unroll") for (int k = 0; k < 2; ++k) \
;         acc[ai][bj][m][n] = __builtin_amdgcn_mfma_f32_16x16x32_bf16(Bt[n][k], At[m][k], acc[ai][bj][m][n], 0, 0, 0); __builtin_amdgcn_s_setprio(0); } while (0)
; #define PG8_WAIT_V(n) asm volatile("s_waitcnt vmcnt(" #n ")" ::: "memory")
; #define PG8_WAIT_L(n) asm volatile("s_waitcnt lgkmcnt(" #n ")" ::: "memory")
; #define PG8_BAR __builtin_amdgcn_s_barrier()
; #define PG8_SCHED __builtin_amdgcn_sched_barrier(0)
; template <class Epi, class Sched, bool ALIGN_EPI = false, bool SP2 = false>
; __device__ __forceinline__ void gemm_phase(PG8_LAS unsigned char* lds, const Gemm g, const Sched& S, const Epi& E) {
;     ...
;             PG8_LDA(At, 1, 1); PG8_STAGE(PG8_SB(1, 0), b3, voffB); PG8_STAGE(PG8_SB(1, 1), b3 + hstep, voffB); PG8_STAGE(PG8_SA(1, 0), a3, voffA);
;             PG8_WAIT_V(8); PG8_WAIT_L(0); PG8_BAR; PG8_MMA(1, 0, At, B0); PG8_MMA(1, 1, At, B1); PG8_BAR; PG8_SCHED;
	s_setprio 1
	s_add_i32 s50, s54, s20
	v_lshl_add_u64 v[178:179], v[178:179], 0, s[36:37]
	s_mov_b32 m0, s50
	ds_read_b128 v[198:201], v151 offset:49152
	ds_read_b128 v[202:205], v151 offset:50176
	ds_read_b128 v[206:209], v151 offset:51200
	ds_read_b128 v[210:213], v151 offset:52224
	ds_read_b128 v[214:217], v151 offset:53248
	ds_read_b128 v[218:221], v151 offset:54272
	ds_read_b128 v[222:225], v151 offset:55296
	ds_read_b128 v[226:229], v151 offset:56320
	global_load_lds_dwordx4 v[178:179], off
	s_add_i32 m0, s50, 0x2000
	s_add_u32 s48, s48, 0x40080
	v_lshl_add_u64 v[178:179], v[230:231], 0, s[36:37]
	s_addc_u32 s49, s49, 0
	s_add_i32 s50, s55, s20
	global_load_lds_dwordx4 v[178:179], off
	v_lshl_add_u64 v[178:179], s[48:49], 0, v[132:133]
	s_mov_b32 m0, s50
	s_nop 0
	global_load_lds_dwordx4 v[178:179], off
	v_lshl_add_u64 v[178:179], s[48:49], 0, v[128:129]
	s_add_i32 m0, s50, 0x2000
	s_nop 0
	global_load_lds_dwordx4 v[178:179], off
	v_lshl_add_u64 v[178:179], v[232:233], 0, s[36:37]
	s_mov_b32 m0, s25
	s_nop 0
	global_load_lds_dwordx4 v[178:179], off
	v_lshl_add_u64 v[178:179], v[234:235], 0, s[36:37]
	s_mov_b32 m0, s28
	s_nop 0
	global_load_lds_dwordx4 v[178:179], off
	s_waitcnt vmcnt(8)
	s_waitcnt lgkmcnt(0)
	s_barrier
	s_setprio 0
	v_mfma_f32_16x16x32_bf16 v[60:63], v[142:145], v[198:201], v[60:63]
	v_mfma_f32_16x16x32_bf16 v[56:59], v[156:159], v[198:201], v[56:59]
	v_mfma_f32_16x16x32_bf16 v[44:47], v[142:145], v[206:209], v[44:47]
	v_mfma_f32_16x16x32_bf16 v[40:43], v[156:159], v[206:209], v[40:43]
	v_mfma_f32_16x16x32_bf16 v[28:31], v[142:145], v[214:217], v[28:31]
	v_mfma_f32_16x16x32_bf16 v[24:27], v[156:159], v[214:217], v[24:27]
	v_mfma_f32_16x16x32_bf16 v[12:15], v[142:145], v[222:225], v[12:15]
	v_mfma_f32_16x16x32_bf16 v[8:11], v[156:159], v[222:225], v[8:11]
	v_mfma_f32_16x16x32_bf16 v[60:63], v[152:155], v[202:205], v[60:63]
	v_mfma_f32_16x16x32_bf16 v[56:59], v[160:163], v[202:205], v[56:59]
	v_mfma_f32_16x16x32_bf16 v[44:47], v[152:155], v[210:213], v[44:47]
	v_mfma_f32_16x16x32_bf16 v[40:43], v[160:163], v[210:213], v[40:43]
	v_mfma_f32_16x16x32_bf16 v[28:31], v[152:155], v[218:221], v[28:31]
	v_mfma_f32_16x16x32_bf16 v[24:27], v[160:163], v[218:221], v[24:27]
	v_mfma_f32_16x16x32_bf16 v[12:15], v[152:155], v[226:229], v[12:15]
	v_mfma_f32_16x16x32_bf16 v[8:11], v[160:163], v[226:229], v[8:11]
	v_mfma_f32_16x16x32_bf16 v[52:55], v[164:167], v[198:201], v[52:55]
	v_mfma_f32_16x16x32_bf16 v[48:51], v[172:175], v[198:201], v[48:51]
	v_mfma_f32_16x16x32_bf16 v[36:39], v[164:167], v[206:209], v[36:39]
	v_mfma_f32_16x16x32_bf16 v[32:35], v[172:175], v[206:209], v[32:35]
	v_mfma_f32_16x16x32_bf16 v[20:23], v[164:167], v[214:217], v[20:23]
	v_mfma_f32_16x16x32_bf16 v[16:19], v[172:175], v[214:217], v[16:19]
	v_mfma_f32_16x16x32_bf16 v[4:7], v[164:167], v[222:225], v[4:7]
	v_mfma_f32_16x16x32_bf16 v[0:3], v[172:175], v[222:225], v[0:3]
	v_mfma_f32_16x16x32_bf16 v[52:55], v[168:171], v[202:205], v[52:55]
	v_mfma_f32_16x16x32_bf16 v[48:51], v[194:197], v[202:205], v[48:51]
	v_mfma_f32_16x16x32_bf16 v[36:39], v[168:171], v[210:213], v[36:39]
	v_mfma_f32_16x16x32_bf16 v[32:35], v[194:197], v[210:213], v[32:35]
	v_mfma_f32_16x16x32_bf16 v[20:23], v[168:171], v[218:221], v[20:23]
	v_mfma_f32_16x16x32_bf16 v[16:19], v[194:197], v[218:221], v[16:19]
	v_mfma_f32_16x16x32_bf16 v[4:7], v[168:171], v[226:229], v[4:7]
	v_mfma_f32_16x16x32_bf16 v[0:3], v[194:197], v[226:229], v[0:3]
	s_barrier
	s_add_i32 s53, s53, 2
	s_add_u32 s41, s41, 0x100
	s_addc_u32 s52, s52, 0
	s_add_u32 s46, s46, 0x100
	s_addc_u32 s47, s47, 0
	s_cmp_gt_u32 s53, 13
	s_cbranch_scc0 .LBB0_659
	s_and_b64 vcc, exec, s[16:17]
	s_cbranch_vccz .LBB0_662
	s_barrier

; #define PG8_STAGE(bufoff, gbase, voff) do { _Pragma("unroll") for (int _i = 0; _i < 2; ++_i) \
;         __builtin_amdgcn_global_load_lds((const unsigned*)((const char*)(gbase) + (voff)[_i]), (PG8_LAS unsigned*)(lds + (bufoff) + ldsw + _i * 8192), 16, 0, 0); } while (0)
; #define PG8_LDA(dst, b, h) do { _Pragma("unroll") for (int m = 0; m < 4; ++m) _Pragma("unroll") for (int k = 0; k < 2; ++k) dst[m][k] = *(const PG8_LAS bf16x8*)(lds + PG8_SA(b, h) + aoff + m * 2048 + k * 1024); } while (0)
; #define PG8_LDB(dst, b, h) do { _Pragma("unroll") for (int n = 0; n < 2; ++n) _Pragma("unroll") for (int k = 0; k < 2; ++k) dst[n][k] = *(const PG8_LAS bf16x8*)(lds + PG8_SB(b, h) + boff + n * 2048 + k * 1024); } while (0)
; #define PG8_MMA(ai, bj, At, Bt) do { __builtin_amdgcn_s_setprio(1); _Pragma("unroll") for (int m = 0; m < 4; ++m) _Pragma("unroll") for (int n = 0; n < 2; ++n) _Pragma("unroll") for (int k = 0; k < 2; ++k) \
;         acc[ai][bj][m][n] = __builtin_amdgcn_mfma_f32_16x16x32_bf16(Bt[n][k], At[m][k], acc[ai][bj][m][n], 0, 0, 0); __builtin_amdgcn_s_setprio(0); } while (0)
; #define PG8_WAIT_V(n) asm volatile("s_waitcnt vmcnt(" #n ")" ::: "memory")
; #define PG8_WAIT_L(n) asm volatile("s_waitcnt lgkmcnt(" #n ")" ::: "memory")
; #define PG8_BAR __builtin_amdgcn_s_barrier()
; #define PG8_SCHED __builtin_amdgcn_sched_barrier(0)
; template <class Epi, class Sched, bool ALIGN_EPI = false, bool SP2 = false>
; __device__ __forceinline__ void gemm_phase(PG8_LAS unsigned char* lds, const Gemm g, const Sched& S, const Epi& E) {
;     ...
;             const bool last = (t == nt - 2);
;             const char* a1 = cA + (size_t)(t + 1) * kstep;
;             const char* a2 = last ? nA : cA + (size_t)(t + 2) * kstep; const char* b2 = last ? nB : cB + (size_t)(t + 2) * kstep;
;             const char* a3 = a2 + kstep; const char* b3 = b2 + kstep;
;             if (last && has_next) S.a_ready(nxt);
;             if constexpr (SP2) {
;             PG8_LDB(B0, 0, 0); PG8_LDB(B1, 0, 1); PG8_SCHED; PG8_LDA(At, 0, 0); PG8_STAGE(PG8_SA(1, 1), a1 + hstep, voffA);
;             PG8_WAIT_V(8); PG8_WAIT_L(0); PG8_BAR; PG8_MMA(0, 0, At, B0); PG8_MMA(0, 1, At, B1); PG8_BAR; PG8_SCHED;
;             PG8_LDA(At, 0, 1); PG8_STAGE(PG8_SB(0, 0), b2, voffB); PG8_STAGE(PG8_SB(0, 1), b2 + hstep, voffB); PG8_STAGE(PG8_SA(0, 0), a2, voffA);
.LBB0_744:
	s_setprio 1
	s_add_u32 s38, s4, 0xfff00080
	s_addc_u32 s39, s5, -1
	s_add_i32 s60, 0, 0x10000
	s_cmp_eq_u32 s59, 60
	s_cselect_b32 s57, s33, s39
	s_cselect_b32 s56, s34, s38
	s_cselect_b32 s39, s35, s58
	s_cselect_b32 s38, s49, s51
	s_add_i32 s62, 0, 0x14000
	v_add_u32_e32 v140, s60, v205
	v_add_u32_e32 v168, s62, v205
	ds_read_b128 v[120:123], v140
	ds_read_b128 v[132:135], v140 offset:1024
	ds_read_b128 v[136:139], v140 offset:2048
	ds_read_b128 v[140:143], v140 offset:3072
	ds_read_b128 v[144:147], v168
	ds_read_b128 v[148:151], v168 offset:1024
	ds_read_b128 v[152:155], v168 offset:2048
	ds_read_b128 v[168:171], v168 offset:3072
	v_lshl_add_u64 v[178:179], s[4:5], 0, v[166:167]
	s_add_i32 m0, s21, 0xc000
	ds_read_b128 v[172:175], v207
	ds_read_b128 v[194:197], v207 offset:1024
	ds_read_b128 v[198:201], v207 offset:2048
	ds_read_b128 v[208:211], v207 offset:3072
	ds_read_b128 v[212:215], v207 offset:4096
	ds_read_b128 v[216:219], v207 offset:5120
	ds_read_b128 v[220:223], v207 offset:6144
	ds_read_b128 v[224:227], v207 offset:7168
	global_load_lds_dwordx4 v[178:179], off
	v_lshl_add_u64 v[178:179], s[4:5], 0, v[164:165]
	s_add_i32 m0, s21, 0xe000
	s_nop 0
	global_load_lds_dwordx4 v[178:179], off
	s_waitcnt vmcnt(8)
	s_waitcnt lgkmcnt(0)
	s_barrier
	s_setprio 0
	v_mfma_f32_16x16x32_bf16 v[128:131], v[120:123], v[172:175], v[128:131]
	v_mfma_f32_16x16x32_bf16 v[124:127], v[136:139], v[172:175], v[124:127]
	v_mfma_f32_16x16x32_bf16 v[108:111], v[120:123], v[198:201], v[108:111]
	v_mfma_f32_16x16x32_bf16 v[104:107], v[136:139], v[198:201], v[104:107]
	v_mfma_f32_16x16x32_bf16 v[92:95], v[120:123], v[212:215], v[92:95]
	v_mfma_f32_16x16x32_bf16 v[88:91], v[136:139], v[212:215], v[88:91]
	v_mfma_f32_16x16x32_bf16 v[76:79], v[120:123], v[220:223], v[76:79]
	v_mfma_f32_16x16x32_bf16 v[72:75], v[136:139], v[220:223], v[72:75]
	v_mfma_f32_16x16x32_bf16 v[128:131], v[132:135], v[194:197], v[128:131]
	v_mfma_f32_16x16x32_bf16 v[124:127], v[140:143], v[194:197], v[124:127]
	v_mfma_f32_16x16x32_bf16 v[108:111], v[132:135], v[208:211], v[108:111]
	v_mfma_f32_16x16x32_bf16 v[104:107], v[140:143], v[208:211], v[104:107]
	v_mfma_f32_16x16x32_bf16 v[92:95], v[132:135], v[216:219], v[92:95]
	v_mfma_f32_16x16x32_bf16 v[88:91], v[140:143], v[216:219], v[88:91]
	v_mfma_f32_16x16x32_bf16 v[76:79], v[132:135], v[224:227], v[76:79]
	v_mfma_f32_16x16x32_bf16 v[72:75], v[140:143], v[224:227], v[72:75]
	v_mfma_f32_16x16x32_bf16 v[116:119], v[144:147], v[172:175], v[116:119]
	v_mfma_f32_16x16x32_bf16 v[112:115], v[152:155], v[172:175], v[112:115]
	v_mfma_f32_16x16x32_bf16 v[100:103], v[144:147], v[198:201], v[100:103]
	v_mfma_f32_16x16x32_bf16 v[96:99], v[152:155], v[198:201], v[96:99]
	v_mfma_f32_16x16x32_bf16 v[84:87], v[144:147], v[212:215], v[84:87]
	v_mfma_f32_16x16x32_bf16 v[80:83], v[152:155], v[212:215], v[80:83]
	v_mfma_f32_16x16x32_bf16 v[68:71], v[144:147], v[220:223], v[68:71]
	v_mfma_f32_16x16x32_bf16 v[64:67], v[152:155], v[220:223], v[64:67]
	v_mfma_f32_16x16x32_bf16 v[116:119], v[148:151], v[194:197], v[116:119]
	v_mfma_f32_16x16x32_bf16 v[112:115], v[168:171], v[194:197], v[112:115]
	v_mfma_f32_16x16x32_bf16 v[100:103], v[148:151], v[208:211], v[100:103]
	v_mfma_f32_16x16x32_bf16 v[96:99], v[168:171], v[208:211], v[96:99]
	v_mfma_f32_16x16x32_bf16 v[84:87], v[148:151], v[216:219], v[84:87]
	v_mfma_f32_16x16x32_bf16 v[80:83], v[168:171], v[216:219], v[80:83]
	v_mfma_f32_16x16x32_bf16 v[68:71], v[148:151], v[224:227], v[68:71]
	v_mfma_f32_16x16x32_bf16 v[64:67], v[168:171], v[224:227], v[64:67]
	s_barrier
	s_setprio 1
	s_add_i32 s60, s60, s20
	v_lshl_add_u64 v[178:179], s[38:39], 0, v[160:161]
	s_mov_b32 m0, s60
	ds_read_b128 v[172:175], v207 offset:16384
	ds_read_b128 v[194:197], v207 offset:17408
	ds_read_b128 v[198:201], v207 offset:18432
	ds_read_b128 v[208:211], v207 offset:19456
	ds_read_b128 v[212:215], v207 offset:20480
	ds_read_b128 v[216:219], v207 offset:21504
	ds_read_b128 v[220:223], v207 offset:22528
	ds_read_b128 v[224:227], v207 offset:23552
	global_load_lds_dwordx4 v[178:179], off
	s_add_i32 m0, s60, 0x2000
	s_add_u32 s60, s38, 0x100000
	v_lshl_add_u64 v[202:203], s[38:39], 0, v[156:157]
	s_addc_u32 s61, s39, 0
	s_add_i32 s62, s62, s20
	global_load_lds_dwordx4 v[202:203], off
	v_lshl_add_u64 v[228:229], s[60:61], 0, v[160:161]
	s_mov_b32 m0, s62
	v_lshl_add_u64 v[230:231], s[56:57], 0, v[158:159]
	global_load_lds_dwordx4 v[228:229], off
	v_lshl_add_u64 v[228:229], s[60:61], 0, v[156:157]
	s_add_i32 m0, s62, 0x2000
	s_nop 0
	global_load_lds_dwordx4 v[228:229], off
	v_lshl_add_u64 v[228:229], s[56:57], 0, v[162:163]
	s_mov_b32 m0, s21
	s_nop 0
	global_load_lds_dwordx4 v[228:229], off
	s_mov_b32 m0, s22
	s_nop 0
	global_load_lds_dwordx4 v[230:231], off
	s_waitcnt vmcnt(8)
	s_waitcnt lgkmcnt(0)
	s_barrier
; #define PG8_STAGE(bufoff, gbase, voff) do { _Pragma("unroll") for (int _i = 0; _i < 2; ++_i) \
;         __builtin_amdgcn_global_load_lds((const unsigned*)((const char*)(gbase) + (voff)[_i]), (PG8_LAS unsigned*)(lds + (bufoff) + ldsw + _i * 8192), 16, 0, 0); } while (0)
; #define PG8_LDA(dst, b, h) do { _Pragma("unroll") for (int m = 0; m < 4; ++m) _Pragma("unroll") for (int k = 0; k < 2; ++k) dst[m][k] = *(const PG8_LAS bf16x8*)(lds + PG8_SA(b, h) + aoff + m * 2048 + k * 1024); } while (0)
; #define PG8_LDB(dst, b, h) do { _Pragma("unroll") for (int n = 0; n < 2; ++n) _Pragma("unroll") for (int k = 0; k < 2; ++k) dst[n][k] = *(const PG8_LAS bf16x8*)(lds + PG8_SB(b, h) + boff + n * 2048 + k * 1024); } while (0)
; #define PG8_MMA(ai, bj, At, Bt) do { __builtin_amdgcn_s_setprio(1); _Pragma("unroll") for (int m = 0; m < 4; ++m) _Pragma("unroll") for (int n = 0; n < 2; ++n) _Pragma("unroll") for (int k = 0; k < 2; ++k) \
;         acc[ai][bj][m][n] = __builtin_amdgcn_mfma_f32_16x16x32_bf16(Bt[n][k], At[m][k], acc[ai][bj][m][n], 0, 0, 0); __builtin_amdgcn_s_setprio(0); } while (0)
; #define PG8_WAIT_V(n) asm volatile("s_waitcnt vmcnt(" #n ")" ::: "memory")
; #define PG8_WAIT_L(n) asm volatile("s_waitcnt lgkmcnt(" #n ")" ::: "memory")
; #define PG8_BAR __builtin_amdgcn_s_barrier()
; #define PG8_SCHED __builtin_amdgcn_sched_barrier(0)
; template <class Epi, class Sched, bool ALIGN_EPI = false, bool SP2 = false>
; __device__ __forceinline__ void gemm_phase(PG8_LAS unsigned char* lds, const Gemm g, const Sched& S, const Epi& E) {
;     ...
;             PG8_LDA(At, 0, 1); PG8_STAGE(PG8_SB(0, 0), b2, voffB); PG8_STAGE(PG8_SB(0, 1), b2 + hstep, voffB); PG8_STAGE(PG8_SA(0, 0), a2, voffA);
;             PG8_WAIT_V(8); PG8_WAIT_L(0); PG8_BAR; PG8_MMA(1, 0, At, B0); PG8_MMA(1, 1, At, B1); PG8_BAR; PG8_SCHED;
;             PG8_LDB(B0, 1, 0); PG8_LDB(B1, 1, 1); PG8_SCHED; PG8_LDA(At, 1, 0); PG8_STAGE(PG8_SA(0, 1), a2 + hstep, voffA);
;             PG8_WAIT_V(8); PG8_WAIT_L(0); PG8_BAR; PG8_MMA(0, 0, At, B0); PG8_MMA(0, 1, At, B1); PG8_BAR; PG8_SCHED;
	s_setprio 0
	v_mfma_f32_16x16x32_bf16 v[60:63], v[120:123], v[172:175], v[60:63]
	v_mfma_f32_16x16x32_bf16 v[56:59], v[136:139], v[172:175], v[56:59]
	v_mfma_f32_16x16x32_bf16 v[44:47], v[120:123], v[198:201], v[44:47]
	v_mfma_f32_16x16x32_bf16 v[40:43], v[136:139], v[198:201], v[40:43]
	v_mfma_f32_16x16x32_bf16 v[28:31], v[120:123], v[212:215], v[28:31]
	v_mfma_f32_16x16x32_bf16 v[24:27], v[136:139], v[212:215], v[24:27]
	v_mfma_f32_16x16x32_bf16 v[12:15], v[120:123], v[220:223], v[12:15]
	v_mfma_f32_16x16x32_bf16 v[8:11], v[136:139], v[220:223], v[8:11]
	v_mfma_f32_16x16x32_bf16 v[60:63], v[132:135], v[194:197], v[60:63]
	v_mfma_f32_16x16x32_bf16 v[56:59], v[140:143], v[194:197], v[56:59]
	v_mfma_f32_16x16x32_bf16 v[44:47], v[132:135], v[208:211], v[44:47]
	v_mfma_f32_16x16x32_bf16 v[40:43], v[140:143], v[208:211], v[40:43]
	v_mfma_f32_16x16x32_bf16 v[28:31], v[132:135], v[216:219], v[28:31]
	v_mfma_f32_16x16x32_bf16 v[24:27], v[140:143], v[216:219], v[24:27]
	v_mfma_f32_16x16x32_bf16 v[12:15], v[132:135], v[224:227], v[12:15]
	v_mfma_f32_16x16x32_bf16 v[8:11], v[140:143], v[224:227], v[8:11]
	v_mfma_f32_16x16x32_bf16 v[52:55], v[144:147], v[172:175], v[52:55]
	v_mfma_f32_16x16x32_bf16 v[48:51], v[152:155], v[172:175], v[48:51]
	v_mfma_f32_16x16x32_bf16 v[36:39], v[144:147], v[198:201], v[36:39]
	v_mfma_f32_16x16x32_bf16 v[32:35], v[152:155], v[198:201], v[32:35]
	v_mfma_f32_16x16x32_bf16 v[20:23], v[144:147], v[212:215], v[20:23]
	v_mfma_f32_16x16x32_bf16 v[16:19], v[152:155], v[212:215], v[16:19]
	v_mfma_f32_16x16x32_bf16 v[4:7], v[144:147], v[220:223], v[4:7]
	v_mfma_f32_16x16x32_bf16 v[0:3], v[152:155], v[220:223], v[0:3]
	v_mfma_f32_16x16x32_bf16 v[52:55], v[148:151], v[194:197], v[52:55]
	v_mfma_f32_16x16x32_bf16 v[48:51], v[168:171], v[194:197], v[48:51]
	v_mfma_f32_16x16x32_bf16 v[36:39], v[148:151], v[208:211], v[36:39]
	v_mfma_f32_16x16x32_bf16 v[32:35], v[168:171], v[208:211], v[32:35]
	v_mfma_f32_16x16x32_bf16 v[20:23], v[148:151], v[216:219], v[20:23]
	v_mfma_f32_16x16x32_bf16 v[16:19], v[168:171], v[216:219], v[16:19]
	v_mfma_f32_16x16x32_bf16 v[4:7], v[148:151], v[224:227], v[4:7]
	v_mfma_f32_16x16x32_bf16 v[0:3], v[168:171], v[224:227], v[0:3]
	s_barrier
	s_setprio 1
	s_add_i32 s60, 0, 0x18000
	s_add_i32 s61, 0, 0x1c000
	v_add_u32_e32 v140, s60, v205
	v_add_u32_e32 v168, s61, v205
	ds_read_b128 v[120:123], v140
	ds_read_b128 v[132:135], v140 offset:1024
	ds_read_b128 v[136:139], v140 offset:2048
	ds_read_b128 v[140:143], v140 offset:3072
	ds_read_b128 v[144:147], v168
	ds_read_b128 v[148:151], v168 offset:1024
	ds_read_b128 v[152:155], v168 offset:2048
	ds_read_b128 v[168:171], v168 offset:3072
	s_add_u32 s56, s56, 0x100000
	s_addc_u32 s57, s57, 0
	s_mov_b32 m0, s23
	v_lshl_add_u64 v[232:233], s[56:57], 0, v[162:163]
	ds_read_b128 v[172:175], v207 offset:32768
	ds_read_b128 v[194:197], v207 offset:33792
	ds_read_b128 v[198:201], v207 offset:34816
	ds_read_b128 v[208:211], v207 offset:35840
	ds_read_b128 v[212:215], v207 offset:36864
	ds_read_b128 v[216:219], v207 offset:37888
	ds_read_b128 v[220:223], v207 offset:38912
	ds_read_b128 v[224:227], v207 offset:39936
	global_load_lds_dwordx4 v[232:233], off
	v_lshl_add_u64 v[232:233], s[56:57], 0, v[158:159]
	s_mov_b32 m0, s24
	s_nop 0
	global_load_lds_dwordx4 v[232:233], off
	s_waitcnt vmcnt(8)
	s_waitcnt lgkmcnt(0)
	s_barrier
	s_setprio 0
	v_mfma_f32_16x16x32_bf16 v[128:131], v[120:123], v[172:175], v[128:131]
	v_mfma_f32_16x16x32_bf16 v[124:127], v[136:139], v[172:175], v[124:127]
	v_mfma_f32_16x16x32_bf16 v[108:111], v[120:123], v[198:201], v[108:111]
	v_mfma_f32_16x16x32_bf16 v[104:107], v[136:139], v[198:201], v[104:107]
	v_mfma_f32_16x16x32_bf16 v[92:95], v[120:123], v[212:215], v[92:95]
	v_mfma_f32_16x16x32_bf16 v[88:91], v[136:139], v[212:215], v[88:91]
	v_mfma_f32_16x16x32_bf16 v[76:79], v[120:123], v[220:223], v[76:79]
	v_mfma_f32_16x16x32_bf16 v[72:75], v[136:139], v[220:223], v[72:75]
	v_mfma_f32_16x16x32_bf16 v[128:131], v[132:135], v[194:197], v[128:131]
	v_mfma_f32_16x16x32_bf16 v[124:127], v[140:143], v[194:197], v[124:127]
	v_mfma_f32_16x16x32_bf16 v[108:111], v[132:135], v[208:211], v[108:111]
	v_mfma_f32_16x16x32_bf16 v[104:107], v[140:143], v[208:211], v[104:107]
	v_mfma_f32_16x16x32_bf16 v[92:95], v[132:135], v[216:219], v[92:95]
	v_mfma_f32_16x16x32_bf16 v[88:91], v[140:143], v[216:219], v[88:91]
	v_mfma_f32_16x16x32_bf16 v[76:79], v[132:135], v[224:227], v[76:79]
	v_mfma_f32_16x16x32_bf16 v[72:75], v[140:143], v[224:227], v[72:75]
	v_mfma_f32_16x16x32_bf16 v[116:119], v[144:147], v[172:175], v[116:119]
	v_mfma_f32_16x16x32_bf16 v[112:115], v[152:155], v[172:175], v[112:115]
	v_mfma_f32_16x16x32_bf16 v[100:103], v[144:147], v[198:201], v[100:103]
	v_mfma_f32_16x16x32_bf16 v[96:99], v[152:155], v[198:201], v[96:99]
	v_mfma_f32_16x16x32_bf16 v[84:87], v[144:147], v[212:215], v[84:87]
	v_mfma_f32_16x16x32_bf16 v[80:83], v[152:155], v[212:215], v[80:83]
	v_mfma_f32_16x16x32_bf16 v[68:71], v[144:147], v[220:223], v[68:71]
	v_mfma_f32_16x16x32_bf16 v[64:67], v[152:155], v[220:223], v[64:67]
	v_mfma_f32_16x16x32_bf16 v[116:119], v[148:151], v[194:197], v[116:119]
	v_mfma_f32_16x16x32_bf16 v[112:115], v[168:171], v[194:197], v[112:115]
	v_mfma_f32_16x16x32_bf16 v[100:103], v[148:151], v[208:211], v[100:103]
	v_mfma_f32_16x16x32_bf16 v[96:99], v[168:171], v[208:211], v[96:99]
	v_mfma_f32_16x16x32_bf16 v[84:87], v[148:151], v[216:219], v[84:87]
	v_mfma_f32_16x16x32_bf16 v[80:83], v[168:171], v[216:219], v[80:83]
	v_mfma_f32_16x16x32_bf16 v[68:71], v[148:151], v[224:227], v[68:71]
	v_mfma_f32_16x16x32_bf16 v[64:67], v[168:171], v[224:227], v[64:67]
	s_barrier
; #define PG8_STAGE(bufoff, gbase, voff) do { _Pragma("unroll") for (int _i = 0; _i < 2; ++_i) \
;         __builtin_amdgcn_global_load_lds((const unsigned*)((const char*)(gbase) + (voff)[_i]), (PG8_LAS unsigned*)(lds + (bufoff) + ldsw + _i * 8192), 16, 0, 0); } while (0)
; #define PG8_LDA(dst, b, h) do { _Pragma("unroll") for (int m = 0; m < 4; ++m) _Pragma("unroll") for (int k = 0; k < 2; ++k) dst[m][k] = *(const PG8_LAS bf16x8*)(lds + PG8_SA(b, h) + aoff + m * 2048 + k * 1024); } while (0)
; #define PG8_MMA(ai, bj, At, Bt) do { __builtin_amdgcn_s_setprio(1); _Pragma("unroll") for (int m = 0; m < 4; ++m) _Pragma("unroll") for (int n = 0; n < 2; ++n) _Pragma("unroll") for (int k = 0; k < 2; ++k) \
;         acc[ai][bj][m][n] = __builtin_amdgcn_mfma_f32_16x16x32_bf16(Bt[n][k], At[m][k], acc[ai][bj][m][n], 0, 0, 0); __builtin_amdgcn_s_setprio(0); } while (0)
; #define PG8_WAIT_V(n) asm volatile("s_waitcnt vmcnt(" #n ")" ::: "memory")
; #define PG8_WAIT_L(n) asm volatile("s_waitcnt lgkmcnt(" #n ")" ::: "memory")
; #define PG8_BAR __builtin_amdgcn_s_barrier()
; #define PG8_SCHED __builtin_amdgcn_sched_barrier(0)
; template <class Epi, class Sched, bool ALIGN_EPI = false, bool SP2 = false>
; __device__ __forceinline__ void gemm_phase(PG8_LAS unsigned char* lds, const Gemm g, const Sched& S, const Epi& E) {
;     ...
;             PG8_LDA(At, 1, 1); PG8_STAGE(PG8_SB(1, 0), b3, voffB); PG8_STAGE(PG8_SB(1, 1), b3 + hstep, voffB); PG8_STAGE(PG8_SA(1, 0), a3, voffA);
;             PG8_WAIT_V(8); PG8_WAIT_L(0); PG8_BAR; PG8_MMA(1, 0, At, B0); PG8_MMA(1, 1, At, B1); PG8_BAR; PG8_SCHED;
	s_setprio 1
	s_add_i32 s56, s60, s20
	v_lshl_add_u64 v[178:179], v[178:179], 0, s[36:37]
	s_mov_b32 m0, s56
	ds_read_b128 v[172:175], v207 offset:49152
	ds_read_b128 v[194:197], v207 offset:50176
	ds_read_b128 v[198:201], v207 offset:51200
	ds_read_b128 v[208:211], v207 offset:52224
	ds_read_b128 v[212:215], v207 offset:53248
	ds_read_b128 v[216:219], v207 offset:54272
	ds_read_b128 v[220:223], v207 offset:55296
	ds_read_b128 v[224:227], v207 offset:56320
	global_load_lds_dwordx4 v[178:179], off
	s_add_i32 m0, s56, 0x2000
	s_add_u32 s38, s38, 0x100080
	v_lshl_add_u64 v[178:179], v[202:203], 0, s[36:37]
	s_addc_u32 s39, s39, 0
	s_add_i32 s56, s61, s20
	global_load_lds_dwordx4 v[178:179], off
	v_lshl_add_u64 v[178:179], s[38:39], 0, v[160:161]
	s_mov_b32 m0, s56
	s_nop 0
	global_load_lds_dwordx4 v[178:179], off
	v_lshl_add_u64 v[178:179], s[38:39], 0, v[156:157]
	s_add_i32 m0, s56, 0x2000
	s_nop 0
	global_load_lds_dwordx4 v[178:179], off
	v_lshl_add_u64 v[178:179], v[228:229], 0, s[36:37]
	s_mov_b32 m0, s29
	s_nop 0
	global_load_lds_dwordx4 v[178:179], off
	v_lshl_add_u64 v[178:179], v[230:231], 0, s[36:37]
	s_mov_b32 m0, s30
	s_nop 0
	global_load_lds_dwordx4 v[178:179], off
	s_waitcnt vmcnt(8)
	s_waitcnt lgkmcnt(0)
	s_barrier
	s_setprio 0
	v_mfma_f32_16x16x32_bf16 v[60:63], v[120:123], v[172:175], v[60:63]
	v_mfma_f32_16x16x32_bf16 v[56:59], v[136:139], v[172:175], v[56:59]
	v_mfma_f32_16x16x32_bf16 v[44:47], v[120:123], v[198:201], v[44:47]
	v_mfma_f32_16x16x32_bf16 v[40:43], v[136:139], v[198:201], v[40:43]
	v_mfma_f32_16x16x32_bf16 v[28:31], v[120:123], v[212:215], v[28:31]
	v_mfma_f32_16x16x32_bf16 v[24:27], v[136:139], v[212:215], v[24:27]
	v_mfma_f32_16x16x32_bf16 v[12:15], v[120:123], v[220:223], v[12:15]
	v_mfma_f32_16x16x32_bf16 v[8:11], v[136:139], v[220:223], v[8:11]
	v_mfma_f32_16x16x32_bf16 v[60:63], v[132:135], v[194:197], v[60:63]
	v_mfma_f32_16x16x32_bf16 v[56:59], v[140:143], v[194:197], v[56:59]
	v_mfma_f32_16x16x32_bf16 v[44:47], v[132:135], v[208:211], v[44:47]
	v_mfma_f32_16x16x32_bf16 v[40:43], v[140:143], v[208:211], v[40:43]
	v_mfma_f32_16x16x32_bf16 v[28:31], v[132:135], v[216:219], v[28:31]
	v_mfma_f32_16x16x32_bf16 v[24:27], v[140:143], v[216:219], v[24:27]
	v_mfma_f32_16x16x32_bf16 v[12:15], v[132:135], v[224:227], v[12:15]
	v_mfma_f32_16x16x32_bf16 v[8:11], v[140:143], v[224:227], v[8:11]
	v_mfma_f32_16x16x32_bf16 v[52:55], v[144:147], v[172:175], v[52:55]
	v_mfma_f32_16x16x32_bf16 v[48:51], v[152:155], v[172:175], v[48:51]
	v_mfma_f32_16x16x32_bf16 v[36:39], v[144:147], v[198:201], v[36:39]
	v_mfma_f32_16x16x32_bf16 v[32:35], v[152:155], v[198:201], v[32:35]
	v_mfma_f32_16x16x32_bf16 v[20:23], v[144:147], v[212:215], v[20:23]
	v_mfma_f32_16x16x32_bf16 v[16:19], v[152:155], v[212:215], v[16:19]
	v_mfma_f32_16x16x32_bf16 v[4:7], v[144:147], v[220:223], v[4:7]
	v_mfma_f32_16x16x32_bf16 v[0:3], v[152:155], v[220:223], v[0:3]
	v_mfma_f32_16x16x32_bf16 v[52:55], v[148:151], v[194:197], v[52:55]
	v_mfma_f32_16x16x32_bf16 v[48:51], v[168:171], v[194:197], v[48:51]
	v_mfma_f32_16x16x32_bf16 v[36:39], v[148:151], v[208:211], v[36:39]
	v_mfma_f32_16x16x32_bf16 v[32:35], v[168:171], v[208:211], v[32:35]
	v_mfma_f32_16x16x32_bf16 v[20:23], v[148:151], v[216:219], v[20:23]
	v_mfma_f32_16x16x32_bf16 v[16:19], v[168:171], v[216:219], v[16:19]
	v_mfma_f32_16x16x32_bf16 v[4:7], v[148:151], v[224:227], v[4:7]
	v_mfma_f32_16x16x32_bf16 v[0:3], v[168:171], v[224:227], v[0:3]
	s_barrier
	s_add_i32 s59, s59, 2
	s_add_u32 s51, s51, 0x100
	s_addc_u32 s58, s58, 0
	s_add_u32 s4, s4, 0x100
	s_addc_u32 s5, s5, 0
	s_cmp_gt_u32 s59, 61
	s_cbranch_scc0 .LBB0_744
	s_and_b64 vcc, exec, s[42:43]
	s_cbranch_vccz .LBB0_747
	s_barrier
